# proj+GU epilogues: permlane16_swap + dwordx4 bf16 stores
# speedup vs baseline: 1.0560x; 1.0138x over previous
; #define G_STAGE(bufoff, gbase, voff) do { _Pragma("unroll") for (int _i = 0; _i < 2; ++_i) \
;     __builtin_amdgcn_global_load_lds((const unsigned*)((const char*)(gbase) + (voff)[_i]), (LAS unsigned*)(lds + (bufoff) + ldsw + _i * 8192), 16, 0, 0); } while (0)
; #define G_LDA(dst, b, h) do { _Pragma("unroll") for (int m = 0; m < 4; ++m) _Pragma("unroll") for (int k = 0; k < 2; ++k) dst[m][k] = *(const LAS bf16x8*)(lds + G_SA(b, h) + aoff + m * 2048 + k * 1024); } while (0)
; #define G_LDB(dst, b, h) do { _Pragma("unroll") for (int n = 0; n < 2; ++n) _Pragma("unroll") for (int k = 0; k < 2; ++k) dst[n][k] = *(const LAS bf16x8*)(lds + G_SB(b, h) + boff + n * 2048 + k * 1024); } while (0)
; #define G_MMA(ai, bj, At, Bt) do { __builtin_amdgcn_s_setprio(1); _Pragma("unroll") for (int m = 0; m < 4; ++m) _Pragma("unroll") for (int n = 0; n < 2; ++n) _Pragma("unroll") for (int k = 0; k < 2; ++k) \
;     acc[ai][bj][m][n] = __builtin_amdgcn_mfma_f32_16x16x32_bf16(Bt[n][k], At[m][k], acc[ai][bj][m][n], 0, 0, 0); __builtin_amdgcn_s_setprio(0); } while (0)
; #define G_WAIT_V(n) asm volatile("s_waitcnt vmcnt(" #n ")" ::: "memory")
; #define G_WAIT_L(n) asm volatile("s_waitcnt lgkmcnt(" #n ")" ::: "memory")
; #define G_BAR __builtin_amdgcn_s_barrier()
; #define G_SCHED __builtin_amdgcn_sched_barrier(0)
; template <class Epi>
; __device__ __forceinline__ void gemm_phase(LAS unsigned char* lds, const u16* gA, const u16* gBt, int M, int N, int K, const Epi& E) {
;     ...
;       G_LDB(B0, 0, 0); G_SCHED; G_LDA(At, 0, 0); G_STAGE(G_SA(1, 1), a1 + hstep, voffA);
;       G_WAIT_L(8); G_BAR; G_WAIT_L(0); G_MMA(0, 0, At, B0); G_BAR; G_SCHED;
;       G_LDB(B1, 0, 1); G_STAGE(G_SB(0, 0), b2, voffB);
;       G_BAR; G_WAIT_L(0); G_MMA(0, 1, At, B1); G_BAR;
;       G_LDA(At, 0, 1); G_STAGE(G_SA(0, 0), a2, voffA);
;       G_BAR; G_WAIT_L(0); G_MMA(1, 0, At, B0); G_BAR; G_SCHED;
;       G_STAGE(G_SB(0, 1), b2 + hstep, voffB);
;       G_WAIT_V(6); G_BAR; G_MMA(1, 1, At, B1); G_BAR;
;       G_LDB(B0, 1, 0); G_SCHED; G_LDA(At, 1, 0); G_STAGE(G_SA(0, 1), a2 + hstep, voffA);
;       G_WAIT_L(8); G_BAR; G_WAIT_L(0); G_MMA(0, 0, At, B0); G_BAR; G_SCHED;
;       G_LDB(B1, 1, 1); G_STAGE(G_SB(1, 0), b3, voffB);
;       G_BAR; G_WAIT_L(0); G_MMA(0, 1, At, B1); G_BAR;
.LBB0_56:
	s_add_u32 s20, s50, 0xfff80080
	s_addc_u32 s22, s51, -1
	s_add_i32 s24, 0, 0x10000
	v_add_u32_e32 v144, s24, v147
	ds_read_b128 v[140:143], v144
	ds_read_b128 v[150:153], v144 offset:1024
	ds_read_b128 v[154:157], v144 offset:2048
	ds_read_b128 v[158:161], v144 offset:3072
	s_cmp_eq_u32 s45, 28
	s_cselect_b32 s55, s26, s22
	s_cselect_b32 s54, s27, s20
	s_cselect_b32 s53, s30, s41
	s_cselect_b32 s52, s31, s33
	v_lshl_add_u64 v[144:145], s[50:51], 0, v[136:137]
	s_add_i32 m0, s3, 0xc000
	ds_read_b128 v[162:165], v149
	ds_read_b128 v[190:193], v149 offset:1024
	ds_read_b128 v[194:197], v149 offset:2048
	ds_read_b128 v[198:201], v149 offset:3072
	ds_read_b128 v[202:205], v149 offset:4096
	ds_read_b128 v[206:209], v149 offset:5120
	ds_read_b128 v[210:213], v149 offset:6144
	ds_read_b128 v[214:217], v149 offset:7168
	global_load_lds_dwordx4 v[144:145], off
	v_lshl_add_u64 v[144:145], s[50:51], 0, v[138:139]
	s_add_i32 m0, s3, 0xe000
	s_nop 0
	global_load_lds_dwordx4 v[144:145], off
	s_waitcnt lgkmcnt(8)
	s_barrier
	s_waitcnt lgkmcnt(0)
	s_setprio 1
	s_waitcnt lgkmcnt(0)
	v_mfma_f32_16x16x32_bf16 v[124:127], v[140:143], v[162:165], v[124:127]
	v_mfma_f32_16x16x32_bf16 v[116:119], v[154:157], v[162:165], v[116:119]
	v_mfma_f32_16x16x32_bf16 v[108:111], v[140:143], v[194:197], v[108:111]
	v_mfma_f32_16x16x32_bf16 v[100:103], v[154:157], v[194:197], v[100:103]
	v_mfma_f32_16x16x32_bf16 v[92:95], v[140:143], v[202:205], v[92:95]
	v_mfma_f32_16x16x32_bf16 v[84:87], v[154:157], v[202:205], v[84:87]
	v_mfma_f32_16x16x32_bf16 v[76:79], v[140:143], v[210:213], v[76:79]
	v_mfma_f32_16x16x32_bf16 v[68:71], v[154:157], v[210:213], v[68:71]
	v_mfma_f32_16x16x32_bf16 v[124:127], v[150:153], v[190:193], v[124:127]
	v_mfma_f32_16x16x32_bf16 v[116:119], v[158:161], v[190:193], v[116:119]
	v_mfma_f32_16x16x32_bf16 v[108:111], v[150:153], v[198:201], v[108:111]
	v_mfma_f32_16x16x32_bf16 v[100:103], v[158:161], v[198:201], v[100:103]
	v_mfma_f32_16x16x32_bf16 v[92:95], v[150:153], v[206:209], v[92:95]
	v_mfma_f32_16x16x32_bf16 v[84:87], v[158:161], v[206:209], v[84:87]
	v_mfma_f32_16x16x32_bf16 v[76:79], v[150:153], v[214:217], v[76:79]
	v_mfma_f32_16x16x32_bf16 v[68:71], v[158:161], v[214:217], v[68:71]
	s_setprio 0
	s_barrier
	s_add_i32 s20, 0, 0x14000
	v_add_u32_e32 v144, s20, v147
	s_add_i32 s22, s24, s64
	ds_read_b128 v[218:221], v144
	ds_read_b128 v[222:225], v144 offset:1024
	ds_read_b128 v[226:229], v144 offset:2048
	ds_read_b128 v[230:233], v144 offset:3072
	v_lshl_add_u64 v[144:145], s[52:53], 0, v[128:129]
	s_mov_b32 m0, s22
	v_lshl_add_u64 v[166:167], s[52:53], 0, v[134:135]
	global_load_lds_dwordx4 v[144:145], off
	s_add_i32 m0, s22, 0x2000
	s_nop 0
	global_load_lds_dwordx4 v[166:167], off
	s_barrier
	s_waitcnt lgkmcnt(0)
	s_setprio 1
	s_waitcnt lgkmcnt(0)
	v_mfma_f32_16x16x32_bf16 v[120:123], v[218:221], v[162:165], v[120:123]
	v_mfma_f32_16x16x32_bf16 v[112:115], v[226:229], v[162:165], v[112:115]
	v_mfma_f32_16x16x32_bf16 v[104:107], v[218:221], v[194:197], v[104:107]
	v_mfma_f32_16x16x32_bf16 v[96:99], v[226:229], v[194:197], v[96:99]
	v_mfma_f32_16x16x32_bf16 v[88:91], v[218:221], v[202:205], v[88:91]
	v_mfma_f32_16x16x32_bf16 v[80:83], v[226:229], v[202:205], v[80:83]
	v_mfma_f32_16x16x32_bf16 v[72:75], v[218:221], v[210:213], v[72:75]
	v_mfma_f32_16x16x32_bf16 v[64:67], v[226:229], v[210:213], v[64:67]
	v_mfma_f32_16x16x32_bf16 v[120:123], v[222:225], v[190:193], v[120:123]
	v_mfma_f32_16x16x32_bf16 v[112:115], v[230:233], v[190:193], v[112:115]
	v_mfma_f32_16x16x32_bf16 v[104:107], v[222:225], v[198:201], v[104:107]
	v_mfma_f32_16x16x32_bf16 v[96:99], v[230:233], v[198:201], v[96:99]
	v_mfma_f32_16x16x32_bf16 v[88:91], v[222:225], v[206:209], v[88:91]
	v_mfma_f32_16x16x32_bf16 v[80:83], v[230:233], v[206:209], v[80:83]
	v_mfma_f32_16x16x32_bf16 v[72:75], v[222:225], v[214:217], v[72:75]
	v_mfma_f32_16x16x32_bf16 v[64:67], v[230:233], v[214:217], v[64:67]
	s_setprio 0
	s_mov_b32 m0, s3
	v_lshl_add_u64 v[234:235], s[54:55], 0, v[128:129]
	s_barrier
	ds_read_b128 v[162:165], v149 offset:16384
	ds_read_b128 v[190:193], v149 offset:17408
	ds_read_b128 v[194:197], v149 offset:18432
	ds_read_b128 v[198:201], v149 offset:19456
	ds_read_b128 v[202:205], v149 offset:20480
	ds_read_b128 v[206:209], v149 offset:21504
	ds_read_b128 v[210:213], v149 offset:22528
	ds_read_b128 v[214:217], v149 offset:23552
	global_load_lds_dwordx4 v[234:235], off
	v_lshl_add_u64 v[236:237], s[54:55], 0, v[134:135]
	s_mov_b32 m0, s67
	s_nop 0
	global_load_lds_dwordx4 v[236:237], off
	s_barrier
	s_waitcnt lgkmcnt(0)
	s_setprio 1
	s_waitcnt lgkmcnt(0)
	v_mfma_f32_16x16x32_bf16 v[60:63], v[140:143], v[162:165], v[60:63]
	v_mfma_f32_16x16x32_bf16 v[52:55], v[154:157], v[162:165], v[52:55]
	v_mfma_f32_16x16x32_bf16 v[44:47], v[140:143], v[194:197], v[44:47]
	v_mfma_f32_16x16x32_bf16 v[36:39], v[154:157], v[194:197], v[36:39]
	v_mfma_f32_16x16x32_bf16 v[28:31], v[140:143], v[202:205], v[28:31]
	v_mfma_f32_16x16x32_bf16 v[20:23], v[154:157], v[202:205], v[20:23]
	v_mfma_f32_16x16x32_bf16 v[12:15], v[140:143], v[210:213], v[12:15]
	v_mfma_f32_16x16x32_bf16 v[4:7], v[154:157], v[210:213], v[4:7]
	v_mfma_f32_16x16x32_bf16 v[60:63], v[150:153], v[190:193], v[60:63]
	v_mfma_f32_16x16x32_bf16 v[52:55], v[158:161], v[190:193], v[52:55]
	v_mfma_f32_16x16x32_bf16 v[44:47], v[150:153], v[198:201], v[44:47]
	v_mfma_f32_16x16x32_bf16 v[36:39], v[158:161], v[198:201], v[36:39]
	v_mfma_f32_16x16x32_bf16 v[28:31], v[150:153], v[206:209], v[28:31]
	v_mfma_f32_16x16x32_bf16 v[20:23], v[158:161], v[206:209], v[20:23]
	v_mfma_f32_16x16x32_bf16 v[12:15], v[150:153], v[214:217], v[12:15]
	v_mfma_f32_16x16x32_bf16 v[4:7], v[158:161], v[214:217], v[4:7]
	s_setprio 0
	s_barrier
; #define G_STAGE(bufoff, gbase, voff) do { _Pragma("unroll") for (int _i = 0; _i < 2; ++_i) \
;     __builtin_amdgcn_global_load_lds((const unsigned*)((const char*)(gbase) + (voff)[_i]), (LAS unsigned*)(lds + (bufoff) + ldsw + _i * 8192), 16, 0, 0); } while (0)
; #define G_LDA(dst, b, h) do { _Pragma("unroll") for (int m = 0; m < 4; ++m) _Pragma("unroll") for (int k = 0; k < 2; ++k) dst[m][k] = *(const LAS bf16x8*)(lds + G_SA(b, h) + aoff + m * 2048 + k * 1024); } while (0)
; #define G_LDB(dst, b, h) do { _Pragma("unroll") for (int n = 0; n < 2; ++n) _Pragma("unroll") for (int k = 0; k < 2; ++k) dst[n][k] = *(const LAS bf16x8*)(lds + G_SB(b, h) + boff + n * 2048 + k * 1024); } while (0)
; #define G_MMA(ai, bj, At, Bt) do { __builtin_amdgcn_s_setprio(1); _Pragma("unroll") for (int m = 0; m < 4; ++m) _Pragma("unroll") for (int n = 0; n < 2; ++n) _Pragma("unroll") for (int k = 0; k < 2; ++k) \
;     acc[ai][bj][m][n] = __builtin_amdgcn_mfma_f32_16x16x32_bf16(Bt[n][k], At[m][k], acc[ai][bj][m][n], 0, 0, 0); __builtin_amdgcn_s_setprio(0); } while (0)
; #define G_WAIT_V(n) asm volatile("s_waitcnt vmcnt(" #n ")" ::: "memory")
; #define G_WAIT_L(n) asm volatile("s_waitcnt lgkmcnt(" #n ")" ::: "memory")
; #define G_BAR __builtin_amdgcn_s_barrier()
; #define G_SCHED __builtin_amdgcn_sched_barrier(0)
; template <class Epi>
; __device__ __forceinline__ void gemm_phase(LAS unsigned char* lds, const u16* gA, const u16* gBt, int M, int N, int K, const Epi& E) {
;     ...
;       G_LDA(At, 0, 1); G_STAGE(G_SA(0, 0), a2, voffA);
;       G_BAR; G_WAIT_L(0); G_MMA(1, 0, At, B0); G_BAR; G_SCHED;
;       G_STAGE(G_SB(0, 1), b2 + hstep, voffB);
;       G_WAIT_V(6); G_BAR; G_MMA(1, 1, At, B1); G_BAR;
;       G_LDB(B0, 1, 0); G_SCHED; G_LDA(At, 1, 0); G_STAGE(G_SA(0, 1), a2 + hstep, voffA);
;       G_WAIT_L(8); G_BAR; G_WAIT_L(0); G_MMA(0, 0, At, B0); G_BAR; G_SCHED;
;       G_LDB(B1, 1, 1); G_STAGE(G_SB(1, 0), b3, voffB);
;       G_BAR; G_WAIT_L(0); G_MMA(0, 1, At, B1); G_BAR;
;       G_LDA(At, 1, 1); G_STAGE(G_SA(1, 0), a3, voffA);
;       G_BAR; G_WAIT_L(0); G_MMA(1, 0, At, B0); G_BAR; G_SCHED;
	s_add_u32 s24, s52, 0x80000
	s_addc_u32 s25, s53, 0
	s_add_i32 s20, s20, s64
	v_lshl_add_u64 v[140:141], s[24:25], 0, v[128:129]
	s_mov_b32 m0, s20
	s_nop 0
	global_load_lds_dwordx4 v[140:141], off
	v_lshl_add_u64 v[140:141], s[24:25], 0, v[134:135]
	s_add_i32 m0, s20, 0x2000
	s_nop 0
	global_load_lds_dwordx4 v[140:141], off
	s_waitcnt vmcnt(6)
	s_barrier
	s_setprio 1
	v_mfma_f32_16x16x32_bf16 v[56:59], v[218:221], v[162:165], v[56:59]
	v_mfma_f32_16x16x32_bf16 v[48:51], v[226:229], v[162:165], v[48:51]
	v_mfma_f32_16x16x32_bf16 v[40:43], v[218:221], v[194:197], v[40:43]
	v_mfma_f32_16x16x32_bf16 v[32:35], v[226:229], v[194:197], v[32:35]
	v_mfma_f32_16x16x32_bf16 v[24:27], v[218:221], v[202:205], v[24:27]
	v_mfma_f32_16x16x32_bf16 v[16:19], v[226:229], v[202:205], v[16:19]
	v_mfma_f32_16x16x32_bf16 v[8:11], v[218:221], v[210:213], v[8:11]
	v_mfma_f32_16x16x32_bf16 v[0:3], v[226:229], v[210:213], v[0:3]
	v_mfma_f32_16x16x32_bf16 v[56:59], v[222:225], v[190:193], v[56:59]
	v_mfma_f32_16x16x32_bf16 v[48:51], v[230:233], v[190:193], v[48:51]
	v_mfma_f32_16x16x32_bf16 v[40:43], v[222:225], v[198:201], v[40:43]
	v_mfma_f32_16x16x32_bf16 v[32:35], v[230:233], v[198:201], v[32:35]
	v_mfma_f32_16x16x32_bf16 v[24:27], v[222:225], v[206:209], v[24:27]
	v_mfma_f32_16x16x32_bf16 v[16:19], v[230:233], v[206:209], v[16:19]
	v_mfma_f32_16x16x32_bf16 v[8:11], v[222:225], v[214:217], v[8:11]
	v_mfma_f32_16x16x32_bf16 v[0:3], v[230:233], v[214:217], v[0:3]
	s_setprio 0
	s_add_i32 s20, 0, 0x18000
	v_add_u32_e32 v158, s20, v147
	s_barrier
	ds_read_b128 v[140:143], v158
	ds_read_b128 v[150:153], v158 offset:1024
	ds_read_b128 v[154:157], v158 offset:2048
	ds_read_b128 v[158:161], v158 offset:3072
	s_add_u32 s24, s54, 0x80000
	s_addc_u32 s25, s55, 0
	s_mov_b32 m0, s68
	v_lshl_add_u64 v[218:219], s[24:25], 0, v[128:129]
	ds_read_b128 v[162:165], v149 offset:32768
	ds_read_b128 v[190:193], v149 offset:33792
	ds_read_b128 v[194:197], v149 offset:34816
	ds_read_b128 v[198:201], v149 offset:35840
	ds_read_b128 v[202:205], v149 offset:36864
	ds_read_b128 v[206:209], v149 offset:37888
	ds_read_b128 v[210:213], v149 offset:38912
	ds_read_b128 v[214:217], v149 offset:39936
	global_load_lds_dwordx4 v[218:219], off
	v_lshl_add_u64 v[218:219], s[24:25], 0, v[134:135]
	s_mov_b32 m0, s69
	s_nop 0
	global_load_lds_dwordx4 v[218:219], off
	s_waitcnt lgkmcnt(8)
	s_barrier
	s_waitcnt lgkmcnt(0)
	s_setprio 1
	s_waitcnt lgkmcnt(0)
	v_mfma_f32_16x16x32_bf16 v[124:127], v[140:143], v[162:165], v[124:127]
	v_mfma_f32_16x16x32_bf16 v[116:119], v[154:157], v[162:165], v[116:119]
	v_mfma_f32_16x16x32_bf16 v[108:111], v[140:143], v[194:197], v[108:111]
	v_mfma_f32_16x16x32_bf16 v[100:103], v[154:157], v[194:197], v[100:103]
	v_mfma_f32_16x16x32_bf16 v[92:95], v[140:143], v[202:205], v[92:95]
	v_mfma_f32_16x16x32_bf16 v[84:87], v[154:157], v[202:205], v[84:87]
	v_mfma_f32_16x16x32_bf16 v[76:79], v[140:143], v[210:213], v[76:79]
	v_mfma_f32_16x16x32_bf16 v[68:71], v[154:157], v[210:213], v[68:71]
	v_mfma_f32_16x16x32_bf16 v[124:127], v[150:153], v[190:193], v[124:127]
	v_mfma_f32_16x16x32_bf16 v[116:119], v[158:161], v[190:193], v[116:119]
	v_mfma_f32_16x16x32_bf16 v[108:111], v[150:153], v[198:201], v[108:111]
	v_mfma_f32_16x16x32_bf16 v[100:103], v[158:161], v[198:201], v[100:103]
	v_mfma_f32_16x16x32_bf16 v[92:95], v[150:153], v[206:209], v[92:95]
	v_mfma_f32_16x16x32_bf16 v[84:87], v[158:161], v[206:209], v[84:87]
	v_mfma_f32_16x16x32_bf16 v[76:79], v[150:153], v[214:217], v[76:79]
	v_mfma_f32_16x16x32_bf16 v[68:71], v[158:161], v[214:217], v[68:71]
	s_setprio 0
	s_barrier
	s_add_i32 s22, 0, 0x1c000
	s_add_i32 s20, s20, s64
	v_add_u32_e32 v230, s22, v147
	v_lshl_add_u64 v[144:145], v[144:145], 0, s[34:35]
	s_mov_b32 m0, s20
	ds_read_b128 v[218:221], v230
	ds_read_b128 v[222:225], v230 offset:1024
	ds_read_b128 v[226:229], v230 offset:2048
	ds_read_b128 v[230:233], v230 offset:3072
	global_load_lds_dwordx4 v[144:145], off
	v_lshl_add_u64 v[144:145], v[166:167], 0, s[34:35]
	s_add_i32 m0, s20, 0x2000
	s_nop 0
	global_load_lds_dwordx4 v[144:145], off
	s_barrier
	s_waitcnt lgkmcnt(0)
	s_setprio 1
	s_waitcnt lgkmcnt(0)
	v_mfma_f32_16x16x32_bf16 v[120:123], v[218:221], v[162:165], v[120:123]
	v_mfma_f32_16x16x32_bf16 v[112:115], v[226:229], v[162:165], v[112:115]
	v_mfma_f32_16x16x32_bf16 v[104:107], v[218:221], v[194:197], v[104:107]
	v_mfma_f32_16x16x32_bf16 v[96:99], v[226:229], v[194:197], v[96:99]
	v_mfma_f32_16x16x32_bf16 v[88:91], v[218:221], v[202:205], v[88:91]
	v_mfma_f32_16x16x32_bf16 v[80:83], v[226:229], v[202:205], v[80:83]
	v_mfma_f32_16x16x32_bf16 v[72:75], v[218:221], v[210:213], v[72:75]
	v_mfma_f32_16x16x32_bf16 v[64:67], v[226:229], v[210:213], v[64:67]
	v_mfma_f32_16x16x32_bf16 v[120:123], v[222:225], v[190:193], v[120:123]
	v_mfma_f32_16x16x32_bf16 v[112:115], v[230:233], v[190:193], v[112:115]
	v_mfma_f32_16x16x32_bf16 v[104:107], v[222:225], v[198:201], v[104:107]
	v_mfma_f32_16x16x32_bf16 v[96:99], v[230:233], v[198:201], v[96:99]
	v_mfma_f32_16x16x32_bf16 v[88:91], v[222:225], v[206:209], v[88:91]
	v_mfma_f32_16x16x32_bf16 v[80:83], v[230:233], v[206:209], v[80:83]
	v_mfma_f32_16x16x32_bf16 v[72:75], v[222:225], v[214:217], v[72:75]
	v_mfma_f32_16x16x32_bf16 v[64:67], v[230:233], v[214:217], v[64:67]
	s_setprio 0
	s_mov_b32 m0, s71
	v_lshl_add_u64 v[144:145], v[234:235], 0, s[34:35]
	s_barrier
	ds_read_b128 v[162:165], v149 offset:49152
	ds_read_b128 v[190:193], v149 offset:50176
	ds_read_b128 v[194:197], v149 offset:51200
	ds_read_b128 v[198:201], v149 offset:52224
	ds_read_b128 v[202:205], v149 offset:53248
	ds_read_b128 v[206:209], v149 offset:54272
	ds_read_b128 v[210:213], v149 offset:55296
	ds_read_b128 v[214:217], v149 offset:56320
	global_load_lds_dwordx4 v[144:145], off
	v_lshl_add_u64 v[144:145], v[236:237], 0, s[34:35]
	s_mov_b32 m0, s72
	s_nop 0
	global_load_lds_dwordx4 v[144:145], off
	s_barrier
; __device__ __forceinline__ float siluf_(float x) { return x / (1.f + __expf(-x)); }
; __device__ __forceinline__ unsigned pk_bf16(float lo, float hi) { return (unsigned)f2bf(lo) | ((unsigned)f2bf(hi) << 16); }
; #define G_STAGE(bufoff, gbase, voff) do { _Pragma("unroll") for (int _i = 0; _i < 2; ++_i) \
;     __builtin_amdgcn_global_load_lds((const unsigned*)((const char*)(gbase) + (voff)[_i]), (LAS unsigned*)(lds + (bufoff) + ldsw + _i * 8192), 16, 0, 0); } while (0)
; #define G_LDA(dst, b, h) do { _Pragma("unroll") for (int m = 0; m < 4; ++m) _Pragma("unroll") for (int k = 0; k < 2; ++k) dst[m][k] = *(const LAS bf16x8*)(lds + G_SA(b, h) + aoff + m * 2048 + k * 1024); } while (0)
; #define G_MMA(ai, bj, At, Bt) do { __builtin_amdgcn_s_setprio(1); _Pragma("unroll") for (int m = 0; m < 4; ++m) _Pragma("unroll") for (int n = 0; n < 2; ++n) _Pragma("unroll") for (int k = 0; k < 2; ++k) \
;     acc[ai][bj][m][n] = __builtin_amdgcn_mfma_f32_16x16x32_bf16(Bt[n][k], At[m][k], acc[ai][bj][m][n], 0, 0, 0); __builtin_amdgcn_s_setprio(0); } while (0)
; #define G_WAIT_V(n) asm volatile("s_waitcnt vmcnt(" #n ")" ::: "memory")
; #define G_WAIT_L(n) asm volatile("s_waitcnt lgkmcnt(" #n ")" ::: "memory")
;   __device__ __forceinline__ void operator()(const f32x4 (&acc)[2][2][4][2], const Unit& u, int wr, int wc, int fr, int fq) const {
;     const int row0 = u.pm * BM + wr * 64 + fr, col0 = u.pn * HALF + wc * 32 + 4 * fq;
; #pragma unroll
;     for (int ai = 0; ai < 2; ++ai)
; #pragma unroll
;       for (int m = 0; m < 4; ++m) {
;         u16* rowp = O + (size_t)(row0 + ai * HALF + m * 16) * FFN + col0;
; #pragma unroll
;         for (int n = 0; n < 2; ++n) {
;           f32x4 g = acc[ai][0][m][n], up = acc[ai][1][m][n];
;           uint2 w;
;           w.x = pk_bf16(siluf_(g[0]) * up[0], siluf_(g[1]) * up[1]);
;           w.y = pk_bf16(siluf_(g[2]) * up[2], siluf_(g[3]) * up[3]);
;           *reinterpret_cast<uint2*>(rowp + n * 16) = w;
;         }
; template <class Epi>
; __device__ __forceinline__ void gemm_phase(LAS unsigned char* lds, const u16* gA, const u16* gBt, int M, int N, int K, const Epi& E) {
;     ...
;       G_LDA(At, 1, 1); G_STAGE(G_SA(1, 0), a3, voffA);
;       G_BAR; G_WAIT_L(0); G_MMA(1, 0, At, B0); G_BAR; G_SCHED;
;       G_STAGE(G_SB(1, 1), b3 + hstep, voffB);
;       G_WAIT_V(6); G_BAR; G_MMA(1, 1, At, B1); G_BAR;
	s_waitcnt lgkmcnt(0)
	s_setprio 1
	s_waitcnt lgkmcnt(0)
	v_mfma_f32_16x16x32_bf16 v[60:63], v[140:143], v[162:165], v[60:63]
	v_mfma_f32_16x16x32_bf16 v[52:55], v[154:157], v[162:165], v[52:55]
	v_mfma_f32_16x16x32_bf16 v[44:47], v[140:143], v[194:197], v[44:47]
	v_mfma_f32_16x16x32_bf16 v[36:39], v[154:157], v[194:197], v[36:39]
	v_mfma_f32_16x16x32_bf16 v[28:31], v[140:143], v[202:205], v[28:31]
	v_mfma_f32_16x16x32_bf16 v[20:23], v[154:157], v[202:205], v[20:23]
	v_mfma_f32_16x16x32_bf16 v[12:15], v[140:143], v[210:213], v[12:15]
	v_mfma_f32_16x16x32_bf16 v[4:7], v[154:157], v[210:213], v[4:7]
	v_mfma_f32_16x16x32_bf16 v[60:63], v[150:153], v[190:193], v[60:63]
	v_mfma_f32_16x16x32_bf16 v[52:55], v[158:161], v[190:193], v[52:55]
	v_mfma_f32_16x16x32_bf16 v[44:47], v[150:153], v[198:201], v[44:47]
	v_mfma_f32_16x16x32_bf16 v[36:39], v[158:161], v[198:201], v[36:39]
	v_mfma_f32_16x16x32_bf16 v[28:31], v[150:153], v[206:209], v[28:31]
	v_mfma_f32_16x16x32_bf16 v[20:23], v[158:161], v[206:209], v[20:23]
	v_mfma_f32_16x16x32_bf16 v[12:15], v[150:153], v[214:217], v[12:15]
	v_mfma_f32_16x16x32_bf16 v[4:7], v[158:161], v[214:217], v[4:7]
	s_setprio 0
	s_barrier
	s_add_u32 s24, s52, 0x80080
	s_addc_u32 s25, s53, 0
	s_add_i32 s20, s22, s64
	v_lshl_add_u64 v[140:141], s[24:25], 0, v[128:129]
	s_mov_b32 m0, s20
	s_nop 0
	global_load_lds_dwordx4 v[140:141], off
	v_lshl_add_u64 v[140:141], s[24:25], 0, v[134:135]
	s_add_i32 m0, s20, 0x2000
	s_nop 0
	global_load_lds_dwordx4 v[140:141], off
	s_waitcnt vmcnt(6)
	s_barrier
	s_setprio 1
	v_mfma_f32_16x16x32_bf16 v[56:59], v[218:221], v[162:165], v[56:59]
	v_mfma_f32_16x16x32_bf16 v[48:51], v[226:229], v[162:165], v[48:51]
	v_mfma_f32_16x16x32_bf16 v[40:43], v[218:221], v[194:197], v[40:43]
	v_mfma_f32_16x16x32_bf16 v[32:35], v[226:229], v[194:197], v[32:35]
	v_mfma_f32_16x16x32_bf16 v[24:27], v[218:221], v[202:205], v[24:27]
	v_mfma_f32_16x16x32_bf16 v[16:19], v[226:229], v[202:205], v[16:19]
	v_mfma_f32_16x16x32_bf16 v[8:11], v[218:221], v[210:213], v[8:11]
	v_mfma_f32_16x16x32_bf16 v[0:3], v[226:229], v[210:213], v[0:3]
	v_mfma_f32_16x16x32_bf16 v[56:59], v[222:225], v[190:193], v[56:59]
	v_mfma_f32_16x16x32_bf16 v[48:51], v[230:233], v[190:193], v[48:51]
	v_mfma_f32_16x16x32_bf16 v[40:43], v[222:225], v[198:201], v[40:43]
	v_mfma_f32_16x16x32_bf16 v[32:35], v[230:233], v[198:201], v[32:35]
	v_mfma_f32_16x16x32_bf16 v[24:27], v[222:225], v[206:209], v[24:27]
	v_mfma_f32_16x16x32_bf16 v[16:19], v[230:233], v[206:209], v[16:19]
	v_mfma_f32_16x16x32_bf16 v[8:11], v[222:225], v[214:217], v[8:11]
	v_mfma_f32_16x16x32_bf16 v[0:3], v[230:233], v[214:217], v[0:3]
	s_setprio 0
	s_add_i32 s45, s45, 2
	s_add_u32 s50, s50, 0x100
	s_addc_u32 s51, s51, 0
	s_add_u32 s33, s33, 0x100
	s_addc_u32 s41, s41, 0
	s_cmp_gt_u32 s45, 29
	s_barrier
	s_cbranch_scc0 .LBB0_56
	v_mul_f32_e32 v151, 0xbfb8aa3b, v124
	v_exp_f32_e32 v152, v151
	v_mul_f32_e32 v151, 0xbfb8aa3b, v125
	v_exp_f32_e32 v154, v151
	v_mul_f32_e32 v151, 0xbfb8aa3b, v126
	v_exp_f32_e32 v153, v151
	v_mul_f32_e32 v151, 0xbfb8aa3b, v127
	v_lshl_or_b32 v142, s23, 7, v148
	v_bfe_u32 v252, v168, 4, 1
	v_mul_u32_u24_e32 v252, 12, v252
	v_add_u32_e32 v142, v142, v252
	v_exp_f32_e32 v155, v151
	v_pk_add_f32 v[152:153], v[152:153], 1.0 op_sel_hi:[1,0]
	v_lshl_add_u32 v150, s2, 8, v146
	v_pk_add_f32 v[154:155], v[154:155], 1.0 op_sel_hi:[1,0]
	v_ashrrev_i32_e32 v143, 31, v142
	v_mov_b64_e32 v[140:141], s[94:95]
	v_rcp_f32_e32 v151, v153
	s_nop 0
	v_mul_f32_e32 v153, v126, v151
	s_movk_i32 s2, 0x2c00
	v_mad_i64_i32 v[144:145], s[22:23], v150, s2, v[140:141]
	v_mov_b32_e32 v156, v120
	v_mov_b32_e32 v157, v122
	v_rcp_f32_e32 v126, v152
	s_nop 0
	v_mul_f32_e32 v152, v124, v126
	v_pk_mul_f32 v[152:153], v[152:153], v[156:157]
	v_lshlrev_b64 v[142:143], 1, v[142:143]
	v_rcp_f32_e32 v120, v155
	s_nop 0
	v_mul_f32_e32 v127, v127, v120
	v_lshl_add_u64 v[144:145], v[144:145], 0, v[142:143]
	s_mov_b64 s[52:53], s[48:49]
	s_mov_b64 s[50:51], s[46:47]
	v_rcp_f32_e32 v120, v154
	s_nop 0
	v_mul_f32_e32 v126, v125, v120
	v_mov_b32_e32 v122, v121
	v_pk_mul_f32 v[120:121], v[126:127], v[122:123]
	s_nop 0
	v_cvt_pk_bf16_f32 v245, v153, v121
	v_cvt_pk_bf16_f32 v244, v152, v120
	v_mul_f32_e32 v121, 0xbfb8aa3b, v117
	v_mul_f32_e32 v120, 0xbfb8aa3b, v116
	v_exp_f32_e32 v122, v121
	v_mul_f32_e32 v121, 0xbfb8aa3b, v118
	v_exp_f32_e32 v120, v120
	v_exp_f32_e32 v121, v121
	v_mul_f32_e32 v123, 0xbfb8aa3b, v119
	v_exp_f32_e32 v123, v123
	v_pk_add_f32 v[120:121], v[120:121], 1.0 op_sel_hi:[1,0]
	s_nop 0
	v_pk_add_f32 v[122:123], v[122:123], 1.0 op_sel_hi:[1,0]
	v_rcp_f32_e32 v124, v121
	s_nop 0
	v_mul_f32_e32 v121, v118, v124
	s_nop 0
	v_mov_b32_e32 v124, v112
	v_mov_b32_e32 v125, v114
	v_rcp_f32_e32 v118, v120
	s_nop 0
	v_mul_f32_e32 v120, v116, v118
	v_pk_mul_f32 v[120:121], v[120:121], v[124:125]
	v_rcp_f32_e32 v112, v123
	s_nop 0
	v_mul_f32_e32 v119, v119, v112
	s_nop 0
	v_rcp_f32_e32 v112, v122
	s_nop 0
	v_mul_f32_e32 v118, v117, v112
	v_mov_b32_e32 v114, v113
	v_pk_mul_f32 v[112:113], v[118:119], v[114:115]
	s_nop 0
	v_cvt_pk_bf16_f32 v246, v120, v112
	v_mul_f32_e32 v115, 0xbfb8aa3b, v109
	v_cvt_pk_bf16_f32 v247, v121, v113
	v_mul_f32_e32 v114, 0xbfb8aa3b, v108
	v_exp_f32_e32 v116, v115
	v_mul_f32_e32 v115, 0xbfb8aa3b, v110
	v_exp_f32_e32 v114, v114
	v_exp_f32_e32 v115, v115
	v_mul_f32_e32 v117, 0xbfb8aa3b, v111
	v_exp_f32_e32 v117, v117
	s_nop 1
	v_permlane16_swap_b32_e32 v244, v246
	v_permlane16_swap_b32_e32 v245, v247
	global_store_dwordx4 v[144:145], v[244:247], off
	v_pk_add_f32 v[114:115], v[114:115], 1.0 op_sel_hi:[1,0]
	v_or_b32_e32 v112, 16, v150
	v_pk_add_f32 v[116:117], v[116:117], 1.0 op_sel_hi:[1,0]
; __device__ __forceinline__ float siluf_(float x) { return x / (1.f + __expf(-x)); }
; __device__ __forceinline__ unsigned pk_bf16(float lo, float hi) { return (unsigned)f2bf(lo) | ((unsigned)f2bf(hi) << 16); }
;   __device__ __forceinline__ void operator()(const f32x4 (&acc)[2][2][4][2], const Unit& u, int wr, int wc, int fr, int fq) const {
;     const int row0 = u.pm * BM + wr * 64 + fr, col0 = u.pn * HALF + wc * 32 + 4 * fq;
; #pragma unroll
;     for (int ai = 0; ai < 2; ++ai)
; #pragma unroll
;       for (int m = 0; m < 4; ++m) {
;         u16* rowp = O + (size_t)(row0 + ai * HALF + m * 16) * FFN + col0;
; #pragma unroll
;         for (int n = 0; n < 2; ++n) {
;           f32x4 g = acc[ai][0][m][n], up = acc[ai][1][m][n];
;           uint2 w;
;           w.x = pk_bf16(siluf_(g[0]) * up[0], siluf_(g[1]) * up[1]);
;           w.y = pk_bf16(siluf_(g[2]) * up[2], siluf_(g[3]) * up[3]);
;           *reinterpret_cast<uint2*>(rowp + n * 16) = w;
;         }
	v_mad_i64_i32 v[112:113], s[22:23], v112, s2, v[140:141]
	v_rcp_f32_e32 v118, v115
	s_nop 0
	v_mul_f32_e32 v115, v110, v118
	v_lshl_add_u64 v[112:113], v[112:113], 0, v[142:143]
	v_mov_b32_e32 v118, v104
	v_mov_b32_e32 v119, v106
	v_rcp_f32_e32 v110, v114
	s_nop 0
	v_mul_f32_e32 v114, v108, v110
	v_pk_mul_f32 v[114:115], v[114:115], v[118:119]
	v_rcp_f32_e32 v104, v117
	s_nop 0
	v_mul_f32_e32 v111, v111, v104
	s_nop 0
	v_rcp_f32_e32 v104, v116
	s_nop 0
	v_mul_f32_e32 v110, v109, v104
	v_mov_b32_e32 v106, v105
	v_pk_mul_f32 v[104:105], v[110:111], v[106:107]
	s_nop 0
	v_cvt_pk_bf16_f32 v249, v115, v105
	v_cvt_pk_bf16_f32 v248, v114, v104
	v_mul_f32_e32 v105, 0xbfb8aa3b, v101
	v_mul_f32_e32 v104, 0xbfb8aa3b, v100
	v_exp_f32_e32 v106, v105
	v_mul_f32_e32 v105, 0xbfb8aa3b, v102
	v_exp_f32_e32 v104, v104
	v_exp_f32_e32 v105, v105
	v_mul_f32_e32 v107, 0xbfb8aa3b, v103
	v_exp_f32_e32 v107, v107
	v_pk_add_f32 v[104:105], v[104:105], 1.0 op_sel_hi:[1,0]
	s_nop 0
	v_pk_add_f32 v[106:107], v[106:107], 1.0 op_sel_hi:[1,0]
	v_rcp_f32_e32 v108, v105
	s_nop 0
	v_mul_f32_e32 v105, v102, v108
	s_nop 0
	v_mov_b32_e32 v108, v96
	v_mov_b32_e32 v109, v98
	v_rcp_f32_e32 v102, v104
	s_nop 0
	v_mul_f32_e32 v104, v100, v102
	v_pk_mul_f32 v[104:105], v[104:105], v[108:109]
	v_rcp_f32_e32 v96, v107
	s_nop 0
	v_mul_f32_e32 v103, v103, v96
	s_nop 0
	v_rcp_f32_e32 v96, v106
	s_nop 0
	v_mul_f32_e32 v102, v101, v96
	v_mov_b32_e32 v98, v97
	v_pk_mul_f32 v[96:97], v[102:103], v[98:99]
	s_nop 0
	v_cvt_pk_bf16_f32 v250, v104, v96
	v_mul_f32_e32 v99, 0xbfb8aa3b, v93
	v_cvt_pk_bf16_f32 v251, v105, v97
	v_mul_f32_e32 v98, 0xbfb8aa3b, v92
	v_exp_f32_e32 v100, v99
	v_mul_f32_e32 v99, 0xbfb8aa3b, v94
	v_exp_f32_e32 v98, v98
	v_exp_f32_e32 v99, v99
	v_mul_f32_e32 v101, 0xbfb8aa3b, v95
	v_exp_f32_e32 v101, v101
	s_nop 1
	v_permlane16_swap_b32_e32 v248, v250
	v_permlane16_swap_b32_e32 v249, v251
	global_store_dwordx4 v[112:113], v[248:251], off
	v_pk_add_f32 v[98:99], v[98:99], 1.0 op_sel_hi:[1,0]
	v_or_b32_e32 v96, 32, v150
	v_pk_add_f32 v[100:101], v[100:101], 1.0 op_sel_hi:[1,0]
	v_mad_i64_i32 v[96:97], s[22:23], v96, s2, v[140:141]
	v_rcp_f32_e32 v102, v99
	s_nop 0
	v_mul_f32_e32 v99, v94, v102
	v_lshl_add_u64 v[96:97], v[96:97], 0, v[142:143]
	v_mov_b32_e32 v102, v88
	v_mov_b32_e32 v103, v90
	v_rcp_f32_e32 v94, v98
	s_nop 0
	v_mul_f32_e32 v98, v92, v94
	v_pk_mul_f32 v[98:99], v[98:99], v[102:103]
	v_rcp_f32_e32 v88, v101
	s_nop 0
	v_mul_f32_e32 v95, v95, v88
	s_nop 0
	v_rcp_f32_e32 v88, v100
	s_nop 0
	v_mul_f32_e32 v94, v93, v88
	v_mov_b32_e32 v90, v89
	v_pk_mul_f32 v[88:89], v[94:95], v[90:91]
	s_nop 0
	v_cvt_pk_bf16_f32 v245, v99, v89
	v_cvt_pk_bf16_f32 v244, v98, v88
	v_mul_f32_e32 v89, 0xbfb8aa3b, v85
	v_mul_f32_e32 v88, 0xbfb8aa3b, v84
	v_exp_f32_e32 v90, v89
	v_mul_f32_e32 v89, 0xbfb8aa3b, v86
	v_exp_f32_e32 v88, v88
	v_exp_f32_e32 v89, v89
	v_mul_f32_e32 v91, 0xbfb8aa3b, v87
	v_exp_f32_e32 v91, v91
	v_pk_add_f32 v[88:89], v[88:89], 1.0 op_sel_hi:[1,0]
	s_nop 0
	v_pk_add_f32 v[90:91], v[90:91], 1.0 op_sel_hi:[1,0]
	v_rcp_f32_e32 v92, v89
	s_nop 0
	v_mul_f32_e32 v89, v86, v92
	s_nop 0
	v_mov_b32_e32 v92, v80
	v_mov_b32_e32 v93, v82
	v_rcp_f32_e32 v86, v88
	s_nop 0
	v_mul_f32_e32 v88, v84, v86
	v_pk_mul_f32 v[88:89], v[88:89], v[92:93]
	v_rcp_f32_e32 v80, v91
	s_nop 0
	v_mul_f32_e32 v87, v87, v80
	s_nop 0
	v_rcp_f32_e32 v80, v90
	s_nop 0
	v_mul_f32_e32 v86, v85, v80
	v_mov_b32_e32 v82, v81
	v_pk_mul_f32 v[80:81], v[86:87], v[82:83]
	s_nop 0
	v_cvt_pk_bf16_f32 v246, v88, v80
	v_mul_f32_e32 v83, 0xbfb8aa3b, v77
	v_cvt_pk_bf16_f32 v247, v89, v81
	v_mul_f32_e32 v82, 0xbfb8aa3b, v76
	v_exp_f32_e32 v84, v83
	v_mul_f32_e32 v83, 0xbfb8aa3b, v78
	v_exp_f32_e32 v82, v82
	v_exp_f32_e32 v83, v83
	v_mul_f32_e32 v85, 0xbfb8aa3b, v79
	v_exp_f32_e32 v85, v85
	s_nop 1
	v_permlane16_swap_b32_e32 v244, v246
	v_permlane16_swap_b32_e32 v245, v247
	global_store_dwordx4 v[96:97], v[244:247], off
	v_pk_add_f32 v[82:83], v[82:83], 1.0 op_sel_hi:[1,0]
	v_or_b32_e32 v80, 48, v150
	v_pk_add_f32 v[84:85], v[84:85], 1.0 op_sel_hi:[1,0]
	v_mad_i64_i32 v[80:81], s[22:23], v80, s2, v[140:141]
	v_rcp_f32_e32 v86, v83
	s_nop 0
	v_mul_f32_e32 v83, v78, v86
	v_lshl_add_u64 v[80:81], v[80:81], 0, v[142:143]
	v_mov_b32_e32 v86, v72
	v_mov_b32_e32 v87, v74
	v_rcp_f32_e32 v78, v82
	s_nop 0
	v_mul_f32_e32 v82, v76, v78
	v_pk_mul_f32 v[82:83], v[82:83], v[86:87]
	v_rcp_f32_e32 v72, v85
	s_nop 0
	v_mul_f32_e32 v79, v79, v72
	s_nop 0
	v_rcp_f32_e32 v72, v84
	s_nop 0
	v_mul_f32_e32 v78, v77, v72
	v_mov_b32_e32 v74, v73
	v_pk_mul_f32 v[72:73], v[78:79], v[74:75]
	s_nop 0
	v_cvt_pk_bf16_f32 v249, v83, v73
	v_cvt_pk_bf16_f32 v248, v82, v72
	v_mul_f32_e32 v73, 0xbfb8aa3b, v69
	v_mul_f32_e32 v72, 0xbfb8aa3b, v68
	v_exp_f32_e32 v74, v73
	v_mul_f32_e32 v73, 0xbfb8aa3b, v70
	v_exp_f32_e32 v72, v72
	v_exp_f32_e32 v73, v73
	v_mul_f32_e32 v75, 0xbfb8aa3b, v71
	v_exp_f32_e32 v75, v75
	v_pk_add_f32 v[72:73], v[72:73], 1.0 op_sel_hi:[1,0]
	s_nop 0
	v_pk_add_f32 v[74:75], v[74:75], 1.0 op_sel_hi:[1,0]
	v_rcp_f32_e32 v76, v73
	s_nop 0
	v_mul_f32_e32 v73, v70, v76
	s_nop 0
	v_mov_b32_e32 v76, v64
	v_mov_b32_e32 v77, v66
	v_rcp_f32_e32 v70, v72
	s_nop 0
	v_mul_f32_e32 v72, v68, v70
	v_pk_mul_f32 v[72:73], v[72:73], v[76:77]
	v_rcp_f32_e32 v64, v75
	s_nop 0
	v_mul_f32_e32 v71, v71, v64
	s_nop 0
	v_rcp_f32_e32 v64, v74
	s_nop 0
	v_mul_f32_e32 v70, v69, v64
	v_mov_b32_e32 v66, v65
	v_pk_mul_f32 v[64:65], v[70:71], v[66:67]
	s_nop 0
	v_cvt_pk_bf16_f32 v250, v72, v64
	v_mul_f32_e32 v67, 0xbfb8aa3b, v61
	v_cvt_pk_bf16_f32 v251, v73, v65
	v_mul_f32_e32 v66, 0xbfb8aa3b, v60
	v_exp_f32_e32 v68, v67
	v_mul_f32_e32 v67, 0xbfb8aa3b, v62
; __device__ __forceinline__ float siluf_(float x) { return x / (1.f + __expf(-x)); }
; __device__ __forceinline__ unsigned pk_bf16(float lo, float hi) { return (unsigned)f2bf(lo) | ((unsigned)f2bf(hi) << 16); }
;   __device__ __forceinline__ void operator()(const f32x4 (&acc)[2][2][4][2], const Unit& u, int wr, int wc, int fr, int fq) const {
;     const int row0 = u.pm * BM + wr * 64 + fr, col0 = u.pn * HALF + wc * 32 + 4 * fq;
; #pragma unroll
;     for (int ai = 0; ai < 2; ++ai)
; #pragma unroll
;       for (int m = 0; m < 4; ++m) {
;         u16* rowp = O + (size_t)(row0 + ai * HALF + m * 16) * FFN + col0;
; #pragma unroll
;         for (int n = 0; n < 2; ++n) {
;           f32x4 g = acc[ai][0][m][n], up = acc[ai][1][m][n];
;           uint2 w;
;           w.x = pk_bf16(siluf_(g[0]) * up[0], siluf_(g[1]) * up[1]);
;           w.y = pk_bf16(siluf_(g[2]) * up[2], siluf_(g[3]) * up[3]);
;           *reinterpret_cast<uint2*>(rowp + n * 16) = w;
;         }
	v_exp_f32_e32 v66, v66
	v_exp_f32_e32 v67, v67
	v_mul_f32_e32 v69, 0xbfb8aa3b, v63
	v_exp_f32_e32 v69, v69
	s_nop 1
	v_permlane16_swap_b32_e32 v248, v250
	v_permlane16_swap_b32_e32 v249, v251
	global_store_dwordx4 v[80:81], v[248:251], off
	v_pk_add_f32 v[66:67], v[66:67], 1.0 op_sel_hi:[1,0]
	v_add_u32_e32 v64, 0x80, v150
	v_pk_add_f32 v[68:69], v[68:69], 1.0 op_sel_hi:[1,0]
	v_mad_i64_i32 v[64:65], s[22:23], v64, s2, v[140:141]
	v_rcp_f32_e32 v70, v67
	s_nop 0
	v_mul_f32_e32 v67, v62, v70
	v_lshl_add_u64 v[64:65], v[64:65], 0, v[142:143]
	v_mov_b32_e32 v70, v56
	v_mov_b32_e32 v71, v58
	v_rcp_f32_e32 v62, v66
	s_nop 0
	v_mul_f32_e32 v66, v60, v62
	v_pk_mul_f32 v[66:67], v[66:67], v[70:71]
	v_rcp_f32_e32 v56, v69
	s_nop 0
	v_mul_f32_e32 v63, v63, v56
	s_nop 0
	v_rcp_f32_e32 v56, v68
	s_nop 0
	v_mul_f32_e32 v62, v61, v56
	v_mov_b32_e32 v58, v57
	v_pk_mul_f32 v[56:57], v[62:63], v[58:59]
	s_nop 0
	v_cvt_pk_bf16_f32 v245, v67, v57
	v_cvt_pk_bf16_f32 v244, v66, v56
	v_mul_f32_e32 v57, 0xbfb8aa3b, v53
	v_mul_f32_e32 v56, 0xbfb8aa3b, v52
	v_exp_f32_e32 v58, v57
	v_mul_f32_e32 v57, 0xbfb8aa3b, v54
	v_exp_f32_e32 v56, v56
	v_exp_f32_e32 v57, v57
	v_mul_f32_e32 v59, 0xbfb8aa3b, v55
	v_exp_f32_e32 v59, v59
	v_pk_add_f32 v[56:57], v[56:57], 1.0 op_sel_hi:[1,0]
	s_nop 0
	v_pk_add_f32 v[58:59], v[58:59], 1.0 op_sel_hi:[1,0]
	v_rcp_f32_e32 v60, v57
	s_nop 0
	v_mul_f32_e32 v57, v54, v60
	s_nop 0
	v_mov_b32_e32 v60, v48
	v_mov_b32_e32 v61, v50
	v_rcp_f32_e32 v54, v56
	s_nop 0
	v_mul_f32_e32 v56, v52, v54
	v_pk_mul_f32 v[56:57], v[56:57], v[60:61]
	v_rcp_f32_e32 v48, v59
	s_nop 0
	v_mul_f32_e32 v55, v55, v48
	s_nop 0
	v_rcp_f32_e32 v48, v58
	s_nop 0
	v_mul_f32_e32 v54, v53, v48
	v_mov_b32_e32 v50, v49
	v_pk_mul_f32 v[48:49], v[54:55], v[50:51]
	s_nop 0
	v_cvt_pk_bf16_f32 v246, v56, v48
	v_mul_f32_e32 v51, 0xbfb8aa3b, v45
	v_cvt_pk_bf16_f32 v247, v57, v49
	v_mul_f32_e32 v50, 0xbfb8aa3b, v44
	v_exp_f32_e32 v52, v51
	v_mul_f32_e32 v51, 0xbfb8aa3b, v46
	v_exp_f32_e32 v50, v50
	v_exp_f32_e32 v51, v51
	v_mul_f32_e32 v53, 0xbfb8aa3b, v47
	v_exp_f32_e32 v53, v53
	s_nop 1
	v_permlane16_swap_b32_e32 v244, v246
	v_permlane16_swap_b32_e32 v245, v247
	global_store_dwordx4 v[64:65], v[244:247], off
	v_pk_add_f32 v[50:51], v[50:51], 1.0 op_sel_hi:[1,0]
	v_add_u32_e32 v48, 0x90, v150
	v_pk_add_f32 v[52:53], v[52:53], 1.0 op_sel_hi:[1,0]
	v_mad_i64_i32 v[48:49], s[22:23], v48, s2, v[140:141]
	v_rcp_f32_e32 v54, v51
	s_nop 0
	v_mul_f32_e32 v51, v46, v54
	v_lshl_add_u64 v[48:49], v[48:49], 0, v[142:143]
	v_mov_b32_e32 v54, v40
	v_mov_b32_e32 v55, v42
	v_rcp_f32_e32 v46, v50
	s_nop 0
	v_mul_f32_e32 v50, v44, v46
	v_pk_mul_f32 v[50:51], v[50:51], v[54:55]
	v_rcp_f32_e32 v40, v53
	s_nop 0
	v_mul_f32_e32 v47, v47, v40
	s_nop 0
	v_rcp_f32_e32 v40, v52
	s_nop 0
	v_mul_f32_e32 v46, v45, v40
	v_mov_b32_e32 v42, v41
	v_pk_mul_f32 v[40:41], v[46:47], v[42:43]
	s_nop 0
	v_cvt_pk_bf16_f32 v249, v51, v41
	v_cvt_pk_bf16_f32 v248, v50, v40
	v_mul_f32_e32 v41, 0xbfb8aa3b, v37
	v_mul_f32_e32 v40, 0xbfb8aa3b, v36
	v_exp_f32_e32 v42, v41
	v_mul_f32_e32 v41, 0xbfb8aa3b, v38
	v_exp_f32_e32 v40, v40
	v_exp_f32_e32 v41, v41
	v_mul_f32_e32 v43, 0xbfb8aa3b, v39
	v_exp_f32_e32 v43, v43
	v_pk_add_f32 v[40:41], v[40:41], 1.0 op_sel_hi:[1,0]
	s_nop 0
	v_pk_add_f32 v[42:43], v[42:43], 1.0 op_sel_hi:[1,0]
	v_rcp_f32_e32 v44, v41
	s_nop 0
	v_mul_f32_e32 v41, v38, v44
	s_nop 0
	v_mov_b32_e32 v44, v32
	v_mov_b32_e32 v45, v34
	v_rcp_f32_e32 v38, v40
	s_nop 0
	v_mul_f32_e32 v40, v36, v38
	v_pk_mul_f32 v[40:41], v[40:41], v[44:45]
	v_rcp_f32_e32 v32, v43
	s_nop 0
	v_mul_f32_e32 v39, v39, v32
	s_nop 0
	v_rcp_f32_e32 v32, v42
	s_nop 0
	v_mul_f32_e32 v38, v37, v32
	v_mov_b32_e32 v34, v33
	v_pk_mul_f32 v[32:33], v[38:39], v[34:35]
	s_nop 0
	v_cvt_pk_bf16_f32 v250, v40, v32
	v_mul_f32_e32 v35, 0xbfb8aa3b, v29
	v_cvt_pk_bf16_f32 v251, v41, v33
	v_mul_f32_e32 v34, 0xbfb8aa3b, v28
	v_exp_f32_e32 v36, v35
	v_mul_f32_e32 v35, 0xbfb8aa3b, v30
	v_exp_f32_e32 v34, v34
	v_exp_f32_e32 v35, v35
; __device__ __forceinline__ float siluf_(float x) { return x / (1.f + __expf(-x)); }
; __device__ __forceinline__ unsigned pk_bf16(float lo, float hi) { return (unsigned)f2bf(lo) | ((unsigned)f2bf(hi) << 16); }
; #define G_WAIT_V(n) asm volatile("s_waitcnt vmcnt(" #n ")" ::: "memory")
; #define G_BAR __builtin_amdgcn_s_barrier()
;   __device__ __forceinline__ void operator()(const f32x4 (&acc)[2][2][4][2], const Unit& u, int wr, int wc, int fr, int fq) const {
;     const int row0 = u.pm * BM + wr * 64 + fr, col0 = u.pn * HALF + wc * 32 + 4 * fq;
; #pragma unroll
;     for (int ai = 0; ai < 2; ++ai)
; #pragma unroll
;       for (int m = 0; m < 4; ++m) {
;         u16* rowp = O + (size_t)(row0 + ai * HALF + m * 16) * FFN + col0;
; #pragma unroll
;         for (int n = 0; n < 2; ++n) {
;           f32x4 g = acc[ai][0][m][n], up = acc[ai][1][m][n];
;           uint2 w;
;           w.x = pk_bf16(siluf_(g[0]) * up[0], siluf_(g[1]) * up[1]);
;           w.y = pk_bf16(siluf_(g[2]) * up[2], siluf_(g[3]) * up[3]);
;           *reinterpret_cast<uint2*>(rowp + n * 16) = w;
;         }
; template <class Epi>
; __device__ __forceinline__ void gemm_phase(LAS unsigned char* lds, const u16* gA, const u16* gBt, int M, int N, int K, const Epi& E) {
;     ...
;     if (!has_next) break;
; #pragma unroll
;     for (int a = 0; a < 2; ++a)
; #pragma unroll
;       for (int b = 0; b < 2; ++b)
; #pragma unroll
;         for (int m = 0; m < 4; ++m)
; #pragma unroll
;           for (int n = 0; n < 2; ++n) acc[a][b][m][n] = (f32x4){0.f, 0.f, 0.f, 0.f};
;     cur = nxt; cA = nA; cB = nB; ++ui;
;   }
;   G_WAIT_V(0);
;   if (wr == 0) G_BAR;
;   G_BAR;
	v_mul_f32_e32 v37, 0xbfb8aa3b, v31
	v_exp_f32_e32 v37, v37
	s_nop 1
	v_permlane16_swap_b32_e32 v248, v250
	v_permlane16_swap_b32_e32 v249, v251
	global_store_dwordx4 v[48:49], v[248:251], off
	v_pk_add_f32 v[34:35], v[34:35], 1.0 op_sel_hi:[1,0]
	v_add_u32_e32 v32, 0xa0, v150
	v_pk_add_f32 v[36:37], v[36:37], 1.0 op_sel_hi:[1,0]
	v_mad_i64_i32 v[32:33], s[22:23], v32, s2, v[140:141]
	v_rcp_f32_e32 v38, v35
	s_nop 0
	v_mul_f32_e32 v35, v30, v38
	v_lshl_add_u64 v[32:33], v[32:33], 0, v[142:143]
	v_mov_b32_e32 v38, v24
	v_mov_b32_e32 v39, v26
	v_rcp_f32_e32 v30, v34
	s_nop 0
	v_mul_f32_e32 v34, v28, v30
	v_pk_mul_f32 v[34:35], v[34:35], v[38:39]
	v_rcp_f32_e32 v24, v37
	s_nop 0
	v_mul_f32_e32 v31, v31, v24
	s_nop 0
	v_rcp_f32_e32 v24, v36
	s_nop 0
	v_mul_f32_e32 v30, v29, v24
	v_mov_b32_e32 v26, v25
	v_pk_mul_f32 v[24:25], v[30:31], v[26:27]
	s_nop 0
	v_cvt_pk_bf16_f32 v245, v35, v25
	v_cvt_pk_bf16_f32 v244, v34, v24
	v_mul_f32_e32 v25, 0xbfb8aa3b, v21
	v_mul_f32_e32 v24, 0xbfb8aa3b, v20
	v_exp_f32_e32 v26, v25
	v_mul_f32_e32 v25, 0xbfb8aa3b, v22
	v_exp_f32_e32 v24, v24
	v_exp_f32_e32 v25, v25
	v_mul_f32_e32 v27, 0xbfb8aa3b, v23
	v_exp_f32_e32 v27, v27
	v_pk_add_f32 v[24:25], v[24:25], 1.0 op_sel_hi:[1,0]
	s_nop 0
	v_pk_add_f32 v[26:27], v[26:27], 1.0 op_sel_hi:[1,0]
	v_rcp_f32_e32 v28, v25
	s_nop 0
	v_mul_f32_e32 v25, v22, v28
	s_nop 0
	v_mov_b32_e32 v28, v16
	v_mov_b32_e32 v29, v18
	v_rcp_f32_e32 v22, v24
	s_nop 0
	v_mul_f32_e32 v24, v20, v22
	v_pk_mul_f32 v[24:25], v[24:25], v[28:29]
	v_rcp_f32_e32 v16, v27
	s_nop 0
	v_mul_f32_e32 v23, v23, v16
	s_nop 0
	v_rcp_f32_e32 v16, v26
	s_nop 0
	v_mul_f32_e32 v22, v21, v16
	v_mov_b32_e32 v18, v17
	v_pk_mul_f32 v[16:17], v[22:23], v[18:19]
	s_nop 0
	v_cvt_pk_bf16_f32 v246, v24, v16
	v_mul_f32_e32 v19, 0xbfb8aa3b, v13
	v_cvt_pk_bf16_f32 v247, v25, v17
	v_mul_f32_e32 v18, 0xbfb8aa3b, v12
	v_exp_f32_e32 v20, v19
	v_mul_f32_e32 v19, 0xbfb8aa3b, v14
	v_exp_f32_e32 v18, v18
	v_exp_f32_e32 v19, v19
	v_mul_f32_e32 v21, 0xbfb8aa3b, v15
	v_exp_f32_e32 v21, v21
	s_nop 1
	v_permlane16_swap_b32_e32 v244, v246
	v_permlane16_swap_b32_e32 v245, v247
	global_store_dwordx4 v[32:33], v[244:247], off
	v_pk_add_f32 v[18:19], v[18:19], 1.0 op_sel_hi:[1,0]
	v_add_u32_e32 v16, 0xb0, v150
	v_pk_add_f32 v[20:21], v[20:21], 1.0 op_sel_hi:[1,0]
	v_mad_i64_i32 v[16:17], s[22:23], v16, s2, v[140:141]
	v_rcp_f32_e32 v22, v19
	s_nop 0
	v_mul_f32_e32 v19, v14, v22
	v_lshl_add_u64 v[16:17], v[16:17], 0, v[142:143]
	s_mov_b32 s2, s44
	v_mov_b32_e32 v22, v8
	v_mov_b32_e32 v23, v10
	v_rcp_f32_e32 v14, v18
	s_nop 0
	v_mul_f32_e32 v18, v12, v14
	v_pk_mul_f32 v[18:19], v[18:19], v[22:23]
	v_rcp_f32_e32 v8, v21
	s_nop 0
	v_mul_f32_e32 v15, v15, v8
	s_nop 0
	v_rcp_f32_e32 v8, v20
	s_nop 0
	v_mul_f32_e32 v14, v13, v8
	v_mov_b32_e32 v10, v9
	v_pk_mul_f32 v[8:9], v[14:15], v[10:11]
	s_nop 0
	v_cvt_pk_bf16_f32 v249, v19, v9
	v_cvt_pk_bf16_f32 v248, v18, v8
	v_mul_f32_e32 v9, 0xbfb8aa3b, v5
	v_mul_f32_e32 v8, 0xbfb8aa3b, v4
	v_exp_f32_e32 v10, v9
	v_mul_f32_e32 v9, 0xbfb8aa3b, v6
	v_exp_f32_e32 v8, v8
	v_exp_f32_e32 v9, v9
	v_mul_f32_e32 v11, 0xbfb8aa3b, v7
	v_exp_f32_e32 v11, v11
	v_pk_add_f32 v[8:9], v[8:9], 1.0 op_sel_hi:[1,0]
	s_nop 0
	v_pk_add_f32 v[10:11], v[10:11], 1.0 op_sel_hi:[1,0]
	v_rcp_f32_e32 v12, v9
	s_nop 0
	v_mul_f32_e32 v9, v6, v12
	s_nop 0
	v_mov_b32_e32 v12, v0
	v_mov_b32_e32 v13, v2
	v_rcp_f32_e32 v6, v8
	s_nop 0
	v_mul_f32_e32 v8, v4, v6
	v_pk_mul_f32 v[8:9], v[8:9], v[12:13]
	v_rcp_f32_e32 v0, v11
	s_nop 0
	v_mul_f32_e32 v7, v7, v0
	s_mov_b32 s23, s40
	v_rcp_f32_e32 v0, v10
	s_nop 0
	v_mul_f32_e32 v6, v5, v0
	v_mov_b32_e32 v2, v1
	v_pk_mul_f32 v[0:1], v[6:7], v[2:3]
	s_nop 0
	v_cvt_pk_bf16_f32 v251, v9, v1
	v_cvt_pk_bf16_f32 v250, v8, v0
	s_and_b64 vcc, exec, s[38:39]
	s_nop 1
	v_permlane16_swap_b32_e32 v248, v250
	v_permlane16_swap_b32_e32 v249, v251
	global_store_dwordx4 v[16:17], v[248:251], off
	s_cbranch_vccz .LBB0_53
	s_waitcnt vmcnt(0)
	s_cmpk_gt_u32 s63, 0xff
	s_cbranch_scc1 .LBB0_60
	s_barrier

; #define G_STAGE(bufoff, gbase, voff) do { _Pragma("unroll") for (int _i = 0; _i < 2; ++_i) \
;     __builtin_amdgcn_global_load_lds((const unsigned*)((const char*)(gbase) + (voff)[_i]), (LAS unsigned*)(lds + (bufoff) + ldsw + _i * 8192), 16, 0, 0); } while (0)
; #define G_LDA(dst, b, h) do { _Pragma("unroll") for (int m = 0; m < 4; ++m) _Pragma("unroll") for (int k = 0; k < 2; ++k) dst[m][k] = *(const LAS bf16x8*)(lds + G_SA(b, h) + aoff + m * 2048 + k * 1024); } while (0)
; #define G_LDB(dst, b, h) do { _Pragma("unroll") for (int n = 0; n < 2; ++n) _Pragma("unroll") for (int k = 0; k < 2; ++k) dst[n][k] = *(const LAS bf16x8*)(lds + G_SB(b, h) + boff + n * 2048 + k * 1024); } while (0)
; #define G_MMA(ai, bj, At, Bt) do { __builtin_amdgcn_s_setprio(1); _Pragma("unroll") for (int m = 0; m < 4; ++m) _Pragma("unroll") for (int n = 0; n < 2; ++n) _Pragma("unroll") for (int k = 0; k < 2; ++k) \
;     acc[ai][bj][m][n] = __builtin_amdgcn_mfma_f32_16x16x32_bf16(Bt[n][k], At[m][k], acc[ai][bj][m][n], 0, 0, 0); __builtin_amdgcn_s_setprio(0); } while (0)
; #define G_WAIT_V(n) asm volatile("s_waitcnt vmcnt(" #n ")" ::: "memory")
; #define G_WAIT_L(n) asm volatile("s_waitcnt lgkmcnt(" #n ")" ::: "memory")
; #define G_BAR __builtin_amdgcn_s_barrier()
; #define G_SCHED __builtin_amdgcn_sched_barrier(0)
; template <class Epi>
; __device__ __forceinline__ void gemm_phase(LAS unsigned char* lds, const u16* gA, const u16* gBt, int M, int N, int K, const Epi& E) {
;     ...
;       G_LDB(B0, 0, 0); G_SCHED; G_LDA(At, 0, 0); G_STAGE(G_SA(1, 1), a1 + hstep, voffA);
;       G_WAIT_L(8); G_BAR; G_WAIT_L(0); G_MMA(0, 0, At, B0); G_BAR; G_SCHED;
;       G_LDB(B1, 0, 1); G_STAGE(G_SB(0, 0), b2, voffB);
;       G_BAR; G_WAIT_L(0); G_MMA(0, 1, At, B1); G_BAR;
;       G_LDA(At, 0, 1); G_STAGE(G_SA(0, 0), a2, voffA);
;       G_BAR; G_WAIT_L(0); G_MMA(1, 0, At, B0); G_BAR; G_SCHED;
;       G_STAGE(G_SB(0, 1), b2 + hstep, voffB);
;       G_WAIT_V(6); G_BAR; G_MMA(1, 1, At, B1); G_BAR;
;       G_LDB(B0, 1, 0); G_SCHED; G_LDA(At, 1, 0); G_STAGE(G_SA(0, 1), a2 + hstep, voffA);
;       G_WAIT_L(8); G_BAR; G_WAIT_L(0); G_MMA(0, 0, At, B0); G_BAR; G_SCHED;
;       G_LDB(B1, 1, 1); G_STAGE(G_SB(1, 0), b3, voffB);
;       G_BAR; G_WAIT_L(0); G_MMA(0, 1, At, B1); G_BAR;
.LBB0_370:
	s_add_u32 s20, s42, 0xfff80080
	s_addc_u32 s22, s43, -1
	s_add_i32 s24, 0, 0x10000
	v_add_u32_e32 v156, s24, v145
	ds_read_b128 v[140:143], v156
	ds_read_b128 v[148:151], v156 offset:1024
	ds_read_b128 v[152:155], v156 offset:2048
	ds_read_b128 v[156:159], v156 offset:3072
	s_cmp_eq_u32 s58, 28
	s_cselect_b32 s47, s3, s22
	s_cselect_b32 s46, s54, s20
	s_cselect_b32 s45, s1, s57
	s_cselect_b32 s44, s55, s56
	v_lshl_add_u64 v[214:215], s[42:43], 0, v[136:137]
	s_add_i32 m0, s27, 0xc000
	ds_read_b128 v[160:163], v147
	ds_read_b128 v[164:167], v147 offset:1024
	ds_read_b128 v[190:193], v147 offset:2048
	ds_read_b128 v[194:197], v147 offset:3072
	ds_read_b128 v[198:201], v147 offset:4096
	ds_read_b128 v[202:205], v147 offset:5120
	ds_read_b128 v[206:209], v147 offset:6144
	ds_read_b128 v[210:213], v147 offset:7168
	global_load_lds_dwordx4 v[214:215], off
	v_lshl_add_u64 v[214:215], s[42:43], 0, v[138:139]
	s_add_i32 m0, s27, 0xe000
	s_nop 0
	global_load_lds_dwordx4 v[214:215], off
	s_waitcnt lgkmcnt(8)
	s_barrier
	s_waitcnt lgkmcnt(0)
	s_setprio 1
	s_waitcnt lgkmcnt(0)
	v_mfma_f32_16x16x32_bf16 v[124:127], v[140:143], v[160:163], v[124:127]
	v_mfma_f32_16x16x32_bf16 v[120:123], v[152:155], v[160:163], v[120:123]
	v_mfma_f32_16x16x32_bf16 v[112:115], v[140:143], v[190:193], v[112:115]
	v_mfma_f32_16x16x32_bf16 v[104:107], v[152:155], v[190:193], v[104:107]
	v_mfma_f32_16x16x32_bf16 v[96:99], v[140:143], v[198:201], v[96:99]
	v_mfma_f32_16x16x32_bf16 v[88:91], v[152:155], v[198:201], v[88:91]
	v_mfma_f32_16x16x32_bf16 v[80:83], v[140:143], v[206:209], v[80:83]
	v_mfma_f32_16x16x32_bf16 v[72:75], v[152:155], v[206:209], v[72:75]
	v_mfma_f32_16x16x32_bf16 v[124:127], v[148:151], v[164:167], v[124:127]
	v_mfma_f32_16x16x32_bf16 v[120:123], v[156:159], v[164:167], v[120:123]
	v_mfma_f32_16x16x32_bf16 v[112:115], v[148:151], v[194:197], v[112:115]
	v_mfma_f32_16x16x32_bf16 v[104:107], v[156:159], v[194:197], v[104:107]
	v_mfma_f32_16x16x32_bf16 v[96:99], v[148:151], v[202:205], v[96:99]
	v_mfma_f32_16x16x32_bf16 v[88:91], v[156:159], v[202:205], v[88:91]
	v_mfma_f32_16x16x32_bf16 v[80:83], v[148:151], v[210:213], v[80:83]
	v_mfma_f32_16x16x32_bf16 v[72:75], v[156:159], v[210:213], v[72:75]
	s_setprio 0
	s_barrier
	s_add_i32 s20, 0, 0x14000
	s_add_i32 s22, s24, s26
	v_add_u32_e32 v226, s20, v145
	v_lshl_add_u64 v[230:231], s[44:45], 0, v[128:129]
	s_mov_b32 m0, s22
	ds_read_b128 v[214:217], v226
	ds_read_b128 v[218:221], v226 offset:1024
	ds_read_b128 v[222:225], v226 offset:2048
	ds_read_b128 v[226:229], v226 offset:3072
	global_load_lds_dwordx4 v[230:231], off
	v_lshl_add_u64 v[232:233], s[44:45], 0, v[134:135]
	s_add_i32 m0, s22, 0x2000
	s_nop 0
	global_load_lds_dwordx4 v[232:233], off
	s_barrier
	s_waitcnt lgkmcnt(0)
	s_setprio 1
	s_waitcnt lgkmcnt(0)
	v_mfma_f32_16x16x32_bf16 v[116:119], v[214:217], v[160:163], v[116:119]
	v_mfma_f32_16x16x32_bf16 v[108:111], v[222:225], v[160:163], v[108:111]
	v_mfma_f32_16x16x32_bf16 v[100:103], v[214:217], v[190:193], v[100:103]
	v_mfma_f32_16x16x32_bf16 v[92:95], v[222:225], v[190:193], v[92:95]
	v_mfma_f32_16x16x32_bf16 v[84:87], v[214:217], v[198:201], v[84:87]
	v_mfma_f32_16x16x32_bf16 v[76:79], v[222:225], v[198:201], v[76:79]
	v_mfma_f32_16x16x32_bf16 v[68:71], v[214:217], v[206:209], v[68:71]
	v_mfma_f32_16x16x32_bf16 v[64:67], v[222:225], v[206:209], v[64:67]
	v_mfma_f32_16x16x32_bf16 v[116:119], v[218:221], v[164:167], v[116:119]
	v_mfma_f32_16x16x32_bf16 v[108:111], v[226:229], v[164:167], v[108:111]
	v_mfma_f32_16x16x32_bf16 v[100:103], v[218:221], v[194:197], v[100:103]
	v_mfma_f32_16x16x32_bf16 v[92:95], v[226:229], v[194:197], v[92:95]
	v_mfma_f32_16x16x32_bf16 v[84:87], v[218:221], v[202:205], v[84:87]
	v_mfma_f32_16x16x32_bf16 v[76:79], v[226:229], v[202:205], v[76:79]
	v_mfma_f32_16x16x32_bf16 v[68:71], v[218:221], v[210:213], v[68:71]
	v_mfma_f32_16x16x32_bf16 v[64:67], v[226:229], v[210:213], v[64:67]
	s_setprio 0
	s_mov_b32 m0, s27
	v_lshl_add_u64 v[234:235], s[46:47], 0, v[128:129]
	s_barrier
	ds_read_b128 v[160:163], v147 offset:16384
	ds_read_b128 v[164:167], v147 offset:17408
	ds_read_b128 v[190:193], v147 offset:18432
	ds_read_b128 v[194:197], v147 offset:19456
	ds_read_b128 v[198:201], v147 offset:20480
	ds_read_b128 v[202:205], v147 offset:21504
	ds_read_b128 v[206:209], v147 offset:22528
	ds_read_b128 v[210:213], v147 offset:23552
	global_load_lds_dwordx4 v[234:235], off
	v_lshl_add_u64 v[236:237], s[46:47], 0, v[134:135]
	s_mov_b32 m0, s28
	s_nop 0
	global_load_lds_dwordx4 v[236:237], off
	s_barrier
	s_waitcnt lgkmcnt(0)
	s_setprio 1
	s_waitcnt lgkmcnt(0)
	v_mfma_f32_16x16x32_bf16 v[60:63], v[140:143], v[160:163], v[60:63]
	v_mfma_f32_16x16x32_bf16 v[56:59], v[152:155], v[160:163], v[56:59]
	v_mfma_f32_16x16x32_bf16 v[48:51], v[140:143], v[190:193], v[48:51]
	v_mfma_f32_16x16x32_bf16 v[40:43], v[152:155], v[190:193], v[40:43]
	v_mfma_f32_16x16x32_bf16 v[32:35], v[140:143], v[198:201], v[32:35]
	v_mfma_f32_16x16x32_bf16 v[24:27], v[152:155], v[198:201], v[24:27]
	v_mfma_f32_16x16x32_bf16 v[16:19], v[140:143], v[206:209], v[16:19]
	v_mfma_f32_16x16x32_bf16 v[8:11], v[152:155], v[206:209], v[8:11]
	v_mfma_f32_16x16x32_bf16 v[60:63], v[148:151], v[164:167], v[60:63]
	v_mfma_f32_16x16x32_bf16 v[56:59], v[156:159], v[164:167], v[56:59]
	v_mfma_f32_16x16x32_bf16 v[48:51], v[148:151], v[194:197], v[48:51]
	v_mfma_f32_16x16x32_bf16 v[40:43], v[156:159], v[194:197], v[40:43]
	v_mfma_f32_16x16x32_bf16 v[32:35], v[148:151], v[202:205], v[32:35]
	v_mfma_f32_16x16x32_bf16 v[24:27], v[156:159], v[202:205], v[24:27]
	v_mfma_f32_16x16x32_bf16 v[16:19], v[148:151], v[210:213], v[16:19]
	v_mfma_f32_16x16x32_bf16 v[8:11], v[156:159], v[210:213], v[8:11]
	s_setprio 0
	s_barrier
; #define G_STAGE(bufoff, gbase, voff) do { _Pragma("unroll") for (int _i = 0; _i < 2; ++_i) \
;     __builtin_amdgcn_global_load_lds((const unsigned*)((const char*)(gbase) + (voff)[_i]), (LAS unsigned*)(lds + (bufoff) + ldsw + _i * 8192), 16, 0, 0); } while (0)
; #define G_LDA(dst, b, h) do { _Pragma("unroll") for (int m = 0; m < 4; ++m) _Pragma("unroll") for (int k = 0; k < 2; ++k) dst[m][k] = *(const LAS bf16x8*)(lds + G_SA(b, h) + aoff + m * 2048 + k * 1024); } while (0)
; #define G_LDB(dst, b, h) do { _Pragma("unroll") for (int n = 0; n < 2; ++n) _Pragma("unroll") for (int k = 0; k < 2; ++k) dst[n][k] = *(const LAS bf16x8*)(lds + G_SB(b, h) + boff + n * 2048 + k * 1024); } while (0)
; #define G_MMA(ai, bj, At, Bt) do { __builtin_amdgcn_s_setprio(1); _Pragma("unroll") for (int m = 0; m < 4; ++m) _Pragma("unroll") for (int n = 0; n < 2; ++n) _Pragma("unroll") for (int k = 0; k < 2; ++k) \
;     acc[ai][bj][m][n] = __builtin_amdgcn_mfma_f32_16x16x32_bf16(Bt[n][k], At[m][k], acc[ai][bj][m][n], 0, 0, 0); __builtin_amdgcn_s_setprio(0); } while (0)
; #define G_WAIT_V(n) asm volatile("s_waitcnt vmcnt(" #n ")" ::: "memory")
; #define G_WAIT_L(n) asm volatile("s_waitcnt lgkmcnt(" #n ")" ::: "memory")
; #define G_BAR __builtin_amdgcn_s_barrier()
; #define G_SCHED __builtin_amdgcn_sched_barrier(0)
; template <class Epi>
; __device__ __forceinline__ void gemm_phase(LAS unsigned char* lds, const u16* gA, const u16* gBt, int M, int N, int K, const Epi& E) {
;     ...
;       G_LDA(At, 0, 1); G_STAGE(G_SA(0, 0), a2, voffA);
;       G_BAR; G_WAIT_L(0); G_MMA(1, 0, At, B0); G_BAR; G_SCHED;
;       G_STAGE(G_SB(0, 1), b2 + hstep, voffB);
;       G_WAIT_V(6); G_BAR; G_MMA(1, 1, At, B1); G_BAR;
;       G_LDB(B0, 1, 0); G_SCHED; G_LDA(At, 1, 0); G_STAGE(G_SA(0, 1), a2 + hstep, voffA);
;       G_WAIT_L(8); G_BAR; G_WAIT_L(0); G_MMA(0, 0, At, B0); G_BAR; G_SCHED;
;       G_LDB(B1, 1, 1); G_STAGE(G_SB(1, 0), b3, voffB);
;       G_BAR; G_WAIT_L(0); G_MMA(0, 1, At, B1); G_BAR;
;       G_LDA(At, 1, 1); G_STAGE(G_SA(1, 0), a3, voffA);
;       G_BAR; G_WAIT_L(0); G_MMA(1, 0, At, B0); G_BAR; G_SCHED;
	s_add_u32 s24, s44, 0x80000
	s_addc_u32 s25, s45, 0
	s_add_i32 s20, s20, s26
	v_lshl_add_u64 v[140:141], s[24:25], 0, v[128:129]
	s_mov_b32 m0, s20
	s_nop 0
	global_load_lds_dwordx4 v[140:141], off
	v_lshl_add_u64 v[140:141], s[24:25], 0, v[134:135]
	s_add_i32 m0, s20, 0x2000
	s_nop 0
	global_load_lds_dwordx4 v[140:141], off
	s_waitcnt vmcnt(6)
	s_barrier
	s_setprio 1
	v_mfma_f32_16x16x32_bf16 v[52:55], v[214:217], v[160:163], v[52:55]
	v_mfma_f32_16x16x32_bf16 v[44:47], v[222:225], v[160:163], v[44:47]
	v_mfma_f32_16x16x32_bf16 v[36:39], v[214:217], v[190:193], v[36:39]
	v_mfma_f32_16x16x32_bf16 v[28:31], v[222:225], v[190:193], v[28:31]
	v_mfma_f32_16x16x32_bf16 v[20:23], v[214:217], v[198:201], v[20:23]
	v_mfma_f32_16x16x32_bf16 v[12:15], v[222:225], v[198:201], v[12:15]
	v_mfma_f32_16x16x32_bf16 v[4:7], v[214:217], v[206:209], v[4:7]
	v_mfma_f32_16x16x32_bf16 v[0:3], v[222:225], v[206:209], v[0:3]
	v_mfma_f32_16x16x32_bf16 v[52:55], v[218:221], v[164:167], v[52:55]
	v_mfma_f32_16x16x32_bf16 v[44:47], v[226:229], v[164:167], v[44:47]
	v_mfma_f32_16x16x32_bf16 v[36:39], v[218:221], v[194:197], v[36:39]
	v_mfma_f32_16x16x32_bf16 v[28:31], v[226:229], v[194:197], v[28:31]
	v_mfma_f32_16x16x32_bf16 v[20:23], v[218:221], v[202:205], v[20:23]
	v_mfma_f32_16x16x32_bf16 v[12:15], v[226:229], v[202:205], v[12:15]
	v_mfma_f32_16x16x32_bf16 v[4:7], v[218:221], v[210:213], v[4:7]
	v_mfma_f32_16x16x32_bf16 v[0:3], v[226:229], v[210:213], v[0:3]
	s_setprio 0
	s_add_i32 s20, 0, 0x18000
	v_add_u32_e32 v156, s20, v145
	s_barrier
	ds_read_b128 v[140:143], v156
	ds_read_b128 v[148:151], v156 offset:1024
	ds_read_b128 v[152:155], v156 offset:2048
	ds_read_b128 v[156:159], v156 offset:3072
	s_add_u32 s24, s46, 0x80000
	s_addc_u32 s25, s47, 0
	s_mov_b32 m0, s33
	v_lshl_add_u64 v[214:215], s[24:25], 0, v[128:129]
	ds_read_b128 v[160:163], v147 offset:32768
	ds_read_b128 v[164:167], v147 offset:33792
	ds_read_b128 v[190:193], v147 offset:34816
	ds_read_b128 v[194:197], v147 offset:35840
	ds_read_b128 v[198:201], v147 offset:36864
	ds_read_b128 v[202:205], v147 offset:37888
	ds_read_b128 v[206:209], v147 offset:38912
	ds_read_b128 v[210:213], v147 offset:39936
	global_load_lds_dwordx4 v[214:215], off
	v_lshl_add_u64 v[214:215], s[24:25], 0, v[134:135]
	s_mov_b32 m0, s48
	s_nop 0
	global_load_lds_dwordx4 v[214:215], off
	s_waitcnt lgkmcnt(8)
	s_barrier
	s_waitcnt lgkmcnt(0)
	s_setprio 1
	s_waitcnt lgkmcnt(0)
	v_mfma_f32_16x16x32_bf16 v[124:127], v[140:143], v[160:163], v[124:127]
	v_mfma_f32_16x16x32_bf16 v[120:123], v[152:155], v[160:163], v[120:123]
	v_mfma_f32_16x16x32_bf16 v[112:115], v[140:143], v[190:193], v[112:115]
	v_mfma_f32_16x16x32_bf16 v[104:107], v[152:155], v[190:193], v[104:107]
	v_mfma_f32_16x16x32_bf16 v[96:99], v[140:143], v[198:201], v[96:99]
	v_mfma_f32_16x16x32_bf16 v[88:91], v[152:155], v[198:201], v[88:91]
	v_mfma_f32_16x16x32_bf16 v[80:83], v[140:143], v[206:209], v[80:83]
	v_mfma_f32_16x16x32_bf16 v[72:75], v[152:155], v[206:209], v[72:75]
	v_mfma_f32_16x16x32_bf16 v[124:127], v[148:151], v[164:167], v[124:127]
	v_mfma_f32_16x16x32_bf16 v[120:123], v[156:159], v[164:167], v[120:123]
	v_mfma_f32_16x16x32_bf16 v[112:115], v[148:151], v[194:197], v[112:115]
	v_mfma_f32_16x16x32_bf16 v[104:107], v[156:159], v[194:197], v[104:107]
	v_mfma_f32_16x16x32_bf16 v[96:99], v[148:151], v[202:205], v[96:99]
	v_mfma_f32_16x16x32_bf16 v[88:91], v[156:159], v[202:205], v[88:91]
	v_mfma_f32_16x16x32_bf16 v[80:83], v[148:151], v[210:213], v[80:83]
	v_mfma_f32_16x16x32_bf16 v[72:75], v[156:159], v[210:213], v[72:75]
	s_setprio 0
	s_barrier
	s_add_i32 s22, 0, 0x1c000
	s_add_i32 s20, s20, s26
	v_add_u32_e32 v226, s22, v145
	v_lshl_add_u64 v[230:231], v[230:231], 0, s[34:35]
	s_mov_b32 m0, s20
	ds_read_b128 v[214:217], v226
	ds_read_b128 v[218:221], v226 offset:1024
	ds_read_b128 v[222:225], v226 offset:2048
	ds_read_b128 v[226:229], v226 offset:3072
	global_load_lds_dwordx4 v[230:231], off
	v_lshl_add_u64 v[230:231], v[232:233], 0, s[34:35]
	s_add_i32 m0, s20, 0x2000
	s_nop 0
	global_load_lds_dwordx4 v[230:231], off
	s_barrier
	s_waitcnt lgkmcnt(0)
	s_setprio 1
	s_waitcnt lgkmcnt(0)
	v_mfma_f32_16x16x32_bf16 v[116:119], v[214:217], v[160:163], v[116:119]
	v_mfma_f32_16x16x32_bf16 v[108:111], v[222:225], v[160:163], v[108:111]
	v_mfma_f32_16x16x32_bf16 v[100:103], v[214:217], v[190:193], v[100:103]
	v_mfma_f32_16x16x32_bf16 v[92:95], v[222:225], v[190:193], v[92:95]
	v_mfma_f32_16x16x32_bf16 v[84:87], v[214:217], v[198:201], v[84:87]
	v_mfma_f32_16x16x32_bf16 v[76:79], v[222:225], v[198:201], v[76:79]
	v_mfma_f32_16x16x32_bf16 v[68:71], v[214:217], v[206:209], v[68:71]
	v_mfma_f32_16x16x32_bf16 v[64:67], v[222:225], v[206:209], v[64:67]
	v_mfma_f32_16x16x32_bf16 v[116:119], v[218:221], v[164:167], v[116:119]
	v_mfma_f32_16x16x32_bf16 v[108:111], v[226:229], v[164:167], v[108:111]
	v_mfma_f32_16x16x32_bf16 v[100:103], v[218:221], v[194:197], v[100:103]
	v_mfma_f32_16x16x32_bf16 v[92:95], v[226:229], v[194:197], v[92:95]
	v_mfma_f32_16x16x32_bf16 v[84:87], v[218:221], v[202:205], v[84:87]
	v_mfma_f32_16x16x32_bf16 v[76:79], v[226:229], v[202:205], v[76:79]
	v_mfma_f32_16x16x32_bf16 v[68:71], v[218:221], v[210:213], v[68:71]
	v_mfma_f32_16x16x32_bf16 v[64:67], v[226:229], v[210:213], v[64:67]
	s_setprio 0
	s_mov_b32 m0, s50
	v_lshl_add_u64 v[230:231], v[234:235], 0, s[34:35]
	s_barrier
	ds_read_b128 v[160:163], v147 offset:49152
	ds_read_b128 v[164:167], v147 offset:50176
	ds_read_b128 v[190:193], v147 offset:51200
	ds_read_b128 v[194:197], v147 offset:52224
	ds_read_b128 v[198:201], v147 offset:53248
	ds_read_b128 v[202:205], v147 offset:54272
	ds_read_b128 v[206:209], v147 offset:55296
	ds_read_b128 v[210:213], v147 offset:56320
	global_load_lds_dwordx4 v[230:231], off
	v_lshl_add_u64 v[230:231], v[236:237], 0, s[34:35]
	s_mov_b32 m0, s51
	s_nop 0
	global_load_lds_dwordx4 v[230:231], off
	s_barrier
; #define G_STAGE(bufoff, gbase, voff) do { _Pragma("unroll") for (int _i = 0; _i < 2; ++_i) \
;     __builtin_amdgcn_global_load_lds((const unsigned*)((const char*)(gbase) + (voff)[_i]), (LAS unsigned*)(lds + (bufoff) + ldsw + _i * 8192), 16, 0, 0); } while (0)
; #define G_LDA(dst, b, h) do { _Pragma("unroll") for (int m = 0; m < 4; ++m) _Pragma("unroll") for (int k = 0; k < 2; ++k) dst[m][k] = *(const LAS bf16x8*)(lds + G_SA(b, h) + aoff + m * 2048 + k * 1024); } while (0)
; #define G_MMA(ai, bj, At, Bt) do { __builtin_amdgcn_s_setprio(1); _Pragma("unroll") for (int m = 0; m < 4; ++m) _Pragma("unroll") for (int n = 0; n < 2; ++n) _Pragma("unroll") for (int k = 0; k < 2; ++k) \
;     acc[ai][bj][m][n] = __builtin_amdgcn_mfma_f32_16x16x32_bf16(Bt[n][k], At[m][k], acc[ai][bj][m][n], 0, 0, 0); __builtin_amdgcn_s_setprio(0); } while (0)
; #define G_WAIT_V(n) asm volatile("s_waitcnt vmcnt(" #n ")" ::: "memory")
; #define G_WAIT_L(n) asm volatile("s_waitcnt lgkmcnt(" #n ")" ::: "memory")
; #define G_BAR __builtin_amdgcn_s_barrier()
; #define G_SCHED __builtin_amdgcn_sched_barrier(0)
; template <class Epi>
; __device__ __forceinline__ void gemm_phase(LAS unsigned char* lds, const u16* gA, const u16* gBt, int M, int N, int K, const Epi& E) {
;     ...
;       G_LDA(At, 1, 1); G_STAGE(G_SA(1, 0), a3, voffA);
;       G_BAR; G_WAIT_L(0); G_MMA(1, 0, At, B0); G_BAR; G_SCHED;
;       G_STAGE(G_SB(1, 1), b3 + hstep, voffB);
;       G_WAIT_V(6); G_BAR; G_MMA(1, 1, At, B1); G_BAR;
	s_waitcnt lgkmcnt(0)
	s_setprio 1
	s_waitcnt lgkmcnt(0)
	v_mfma_f32_16x16x32_bf16 v[60:63], v[140:143], v[160:163], v[60:63]
	v_mfma_f32_16x16x32_bf16 v[56:59], v[152:155], v[160:163], v[56:59]
	v_mfma_f32_16x16x32_bf16 v[48:51], v[140:143], v[190:193], v[48:51]
	v_mfma_f32_16x16x32_bf16 v[40:43], v[152:155], v[190:193], v[40:43]
	v_mfma_f32_16x16x32_bf16 v[32:35], v[140:143], v[198:201], v[32:35]
	v_mfma_f32_16x16x32_bf16 v[24:27], v[152:155], v[198:201], v[24:27]
	v_mfma_f32_16x16x32_bf16 v[16:19], v[140:143], v[206:209], v[16:19]
	v_mfma_f32_16x16x32_bf16 v[8:11], v[152:155], v[206:209], v[8:11]
	v_mfma_f32_16x16x32_bf16 v[60:63], v[148:151], v[164:167], v[60:63]
	v_mfma_f32_16x16x32_bf16 v[56:59], v[156:159], v[164:167], v[56:59]
	v_mfma_f32_16x16x32_bf16 v[48:51], v[148:151], v[194:197], v[48:51]
	v_mfma_f32_16x16x32_bf16 v[40:43], v[156:159], v[194:197], v[40:43]
	v_mfma_f32_16x16x32_bf16 v[32:35], v[148:151], v[202:205], v[32:35]
	v_mfma_f32_16x16x32_bf16 v[24:27], v[156:159], v[202:205], v[24:27]
	v_mfma_f32_16x16x32_bf16 v[16:19], v[148:151], v[210:213], v[16:19]
	v_mfma_f32_16x16x32_bf16 v[8:11], v[156:159], v[210:213], v[8:11]
	s_setprio 0
	s_barrier
	s_add_u32 s24, s44, 0x80080
	s_addc_u32 s25, s45, 0
	s_add_i32 s20, s22, s26
	v_lshl_add_u64 v[140:141], s[24:25], 0, v[128:129]
	s_mov_b32 m0, s20
	s_nop 0
	global_load_lds_dwordx4 v[140:141], off
	v_lshl_add_u64 v[140:141], s[24:25], 0, v[134:135]
	s_add_i32 m0, s20, 0x2000
	s_nop 0
	global_load_lds_dwordx4 v[140:141], off
	s_waitcnt vmcnt(6)
	s_barrier
	s_setprio 1
	v_mfma_f32_16x16x32_bf16 v[52:55], v[214:217], v[160:163], v[52:55]
	v_mfma_f32_16x16x32_bf16 v[44:47], v[222:225], v[160:163], v[44:47]
	v_mfma_f32_16x16x32_bf16 v[36:39], v[214:217], v[190:193], v[36:39]
	v_mfma_f32_16x16x32_bf16 v[28:31], v[222:225], v[190:193], v[28:31]
	v_mfma_f32_16x16x32_bf16 v[20:23], v[214:217], v[198:201], v[20:23]
	v_mfma_f32_16x16x32_bf16 v[12:15], v[222:225], v[198:201], v[12:15]
	v_mfma_f32_16x16x32_bf16 v[4:7], v[214:217], v[206:209], v[4:7]
	v_mfma_f32_16x16x32_bf16 v[0:3], v[222:225], v[206:209], v[0:3]
	v_mfma_f32_16x16x32_bf16 v[52:55], v[218:221], v[164:167], v[52:55]
	v_mfma_f32_16x16x32_bf16 v[44:47], v[226:229], v[164:167], v[44:47]
	v_mfma_f32_16x16x32_bf16 v[36:39], v[218:221], v[194:197], v[36:39]
	v_mfma_f32_16x16x32_bf16 v[28:31], v[226:229], v[194:197], v[28:31]
	v_mfma_f32_16x16x32_bf16 v[20:23], v[218:221], v[202:205], v[20:23]
	v_mfma_f32_16x16x32_bf16 v[12:15], v[226:229], v[202:205], v[12:15]
	v_mfma_f32_16x16x32_bf16 v[4:7], v[218:221], v[210:213], v[4:7]
	v_mfma_f32_16x16x32_bf16 v[0:3], v[226:229], v[210:213], v[0:3]
	s_setprio 0
	s_add_i32 s58, s58, 2
	s_add_u32 s42, s42, 0x100
	s_addc_u32 s43, s43, 0
	s_add_u32 s56, s56, 0x100
	s_addc_u32 s57, s57, 0
	s_cmp_gt_u32 s58, 29
	s_barrier
	s_cbranch_scc0 .LBB0_370
; __device__ __forceinline__ unsigned pk_bf16(float lo, float hi) { return (unsigned)f2bf(lo) | ((unsigned)f2bf(hi) << 16); }
;   __device__ __forceinline__ void operator()(const f32x4 (&acc)[2][2][4][2], const Unit& u, int wr, int wc, int fr, int fq) const {
;     const int row0 = u.pm * BM + wr * 64 + fr, col0 = u.pn * BM + wc * 32 + 4 * fq;
; #pragma unroll
;     for (int ai = 0; ai < 2; ++ai)
; #pragma unroll
;       for (int m = 0; m < 4; ++m) {
;         u16* rowp = O + (size_t)(row0 + ai * HALF + m * 16) * PROJP + col0;
; #pragma unroll
;         for (int bj = 0; bj < 2; ++bj)
; #pragma unroll
;           for (int n = 0; n < 2; ++n) {
;             f32x4 v = acc[ai][bj][m][n];
;             uint2 w; w.x = pk_bf16(v[0], v[1]); w.y = pk_bf16(v[2], v[3]);
;             *reinterpret_cast<uint2*>(rowp + bj * HALF + n * 16) = w;
;           }
;       }
;   }
	v_lshl_or_b32 v142, s30, 8, v146
	v_lshl_add_u32 v150, s31, 8, v144
	v_bfe_u32 v151, v168, 4, 1
	v_mul_u32_u24_e32 v151, 12, v151
	v_add_u32_e32 v142, v142, v151
	v_ashrrev_i32_e32 v143, 31, v142
	v_mov_b64_e32 v[140:141], s[94:95]
	s_movk_i32 s1, 0x3600
	v_lshlrev_b64 v[142:143], 1, v[142:143]
	v_mad_i64_i32 v[148:149], s[24:25], v150, s1, v[140:141]
	v_lshl_add_u64 v[148:149], v[148:149], 0, v[142:143]
	v_cvt_pk_bf16_f32 v124, v124, v125
	v_cvt_pk_bf16_f32 v125, v126, v127
	v_cvt_pk_bf16_f32 v126, v120, v121
	v_cvt_pk_bf16_f32 v127, v122, v123
	s_nop 1
	v_permlane16_swap_b32_e32 v124, v126
	v_permlane16_swap_b32_e32 v125, v127
	global_store_dwordx4 v[148:149], v[124:127], off
	v_cvt_pk_bf16_f32 v116, v116, v117
	v_cvt_pk_bf16_f32 v117, v118, v119
	v_cvt_pk_bf16_f32 v118, v108, v109
	v_cvt_pk_bf16_f32 v119, v110, v111
	s_nop 1
	v_permlane16_swap_b32_e32 v116, v118
	v_permlane16_swap_b32_e32 v117, v119
	global_store_dwordx4 v[148:149], v[116:119], off offset:256
	v_add_u32_e32 v152, 0x10, v150
	v_mad_i64_i32 v[148:149], s[24:25], v152, s1, v[140:141]
	v_lshl_add_u64 v[148:149], v[148:149], 0, v[142:143]
	v_cvt_pk_bf16_f32 v112, v112, v113
	v_cvt_pk_bf16_f32 v113, v114, v115
	v_cvt_pk_bf16_f32 v114, v104, v105
	v_cvt_pk_bf16_f32 v115, v106, v107
	s_nop 1
	v_permlane16_swap_b32_e32 v112, v114
	v_permlane16_swap_b32_e32 v113, v115
	global_store_dwordx4 v[148:149], v[112:115], off
	v_cvt_pk_bf16_f32 v100, v100, v101
	v_cvt_pk_bf16_f32 v101, v102, v103
	v_cvt_pk_bf16_f32 v102, v92, v93
	v_cvt_pk_bf16_f32 v103, v94, v95
	s_nop 1
	v_permlane16_swap_b32_e32 v100, v102
	v_permlane16_swap_b32_e32 v101, v103
	global_store_dwordx4 v[148:149], v[100:103], off offset:256
	v_add_u32_e32 v152, 0x20, v150
	v_mad_i64_i32 v[148:149], s[24:25], v152, s1, v[140:141]
	v_lshl_add_u64 v[148:149], v[148:149], 0, v[142:143]
	v_cvt_pk_bf16_f32 v96, v96, v97
	v_cvt_pk_bf16_f32 v97, v98, v99
	v_cvt_pk_bf16_f32 v98, v88, v89
	v_cvt_pk_bf16_f32 v99, v90, v91
	s_nop 1
	v_permlane16_swap_b32_e32 v96, v98
	v_permlane16_swap_b32_e32 v97, v99
	global_store_dwordx4 v[148:149], v[96:99], off
	v_cvt_pk_bf16_f32 v84, v84, v85
	v_cvt_pk_bf16_f32 v85, v86, v87
	v_cvt_pk_bf16_f32 v86, v76, v77
	v_cvt_pk_bf16_f32 v87, v78, v79
	s_nop 1
	v_permlane16_swap_b32_e32 v84, v86
	v_permlane16_swap_b32_e32 v85, v87
	global_store_dwordx4 v[148:149], v[84:87], off offset:256
	v_add_u32_e32 v152, 0x30, v150
	v_mad_i64_i32 v[148:149], s[24:25], v152, s1, v[140:141]
	v_lshl_add_u64 v[148:149], v[148:149], 0, v[142:143]
	v_cvt_pk_bf16_f32 v80, v80, v81
	v_cvt_pk_bf16_f32 v81, v82, v83
	v_cvt_pk_bf16_f32 v82, v72, v73
	v_cvt_pk_bf16_f32 v83, v74, v75
	s_nop 1
	v_permlane16_swap_b32_e32 v80, v82
	v_permlane16_swap_b32_e32 v81, v83
	global_store_dwordx4 v[148:149], v[80:83], off
	v_cvt_pk_bf16_f32 v68, v68, v69
	v_cvt_pk_bf16_f32 v69, v70, v71
	v_cvt_pk_bf16_f32 v70, v64, v65
	v_cvt_pk_bf16_f32 v71, v66, v67
	s_nop 1
	v_permlane16_swap_b32_e32 v68, v70
	v_permlane16_swap_b32_e32 v69, v71
	global_store_dwordx4 v[148:149], v[68:71], off offset:256
	v_add_u32_e32 v152, 0x80, v150
	v_mad_i64_i32 v[148:149], s[24:25], v152, s1, v[140:141]
	v_lshl_add_u64 v[148:149], v[148:149], 0, v[142:143]
	v_cvt_pk_bf16_f32 v60, v60, v61
	v_cvt_pk_bf16_f32 v61, v62, v63
	v_cvt_pk_bf16_f32 v62, v56, v57
	v_cvt_pk_bf16_f32 v63, v58, v59
	s_nop 1
	v_permlane16_swap_b32_e32 v60, v62
	v_permlane16_swap_b32_e32 v61, v63
	global_store_dwordx4 v[148:149], v[60:63], off
	v_cvt_pk_bf16_f32 v52, v52, v53
	v_cvt_pk_bf16_f32 v53, v54, v55
	v_cvt_pk_bf16_f32 v54, v44, v45
	v_cvt_pk_bf16_f32 v55, v46, v47
	s_nop 1
	v_permlane16_swap_b32_e32 v52, v54
	v_permlane16_swap_b32_e32 v53, v55
	global_store_dwordx4 v[148:149], v[52:55], off offset:256
	v_add_u32_e32 v152, 0x90, v150
	v_mad_i64_i32 v[148:149], s[24:25], v152, s1, v[140:141]
	v_lshl_add_u64 v[148:149], v[148:149], 0, v[142:143]
	v_cvt_pk_bf16_f32 v48, v48, v49
	v_cvt_pk_bf16_f32 v49, v50, v51
	v_cvt_pk_bf16_f32 v50, v40, v41
	v_cvt_pk_bf16_f32 v51, v42, v43
	s_nop 1
	v_permlane16_swap_b32_e32 v48, v50
	v_permlane16_swap_b32_e32 v49, v51
	global_store_dwordx4 v[148:149], v[48:51], off
	v_cvt_pk_bf16_f32 v36, v36, v37
	v_cvt_pk_bf16_f32 v37, v38, v39
	v_cvt_pk_bf16_f32 v38, v28, v29
	v_cvt_pk_bf16_f32 v39, v30, v31
	s_nop 1
	v_permlane16_swap_b32_e32 v36, v38
	v_permlane16_swap_b32_e32 v37, v39
	global_store_dwordx4 v[148:149], v[36:39], off offset:256
	v_add_u32_e32 v152, 0xa0, v150
	v_mad_i64_i32 v[148:149], s[24:25], v152, s1, v[140:141]
	v_lshl_add_u64 v[148:149], v[148:149], 0, v[142:143]
	v_cvt_pk_bf16_f32 v32, v32, v33
	v_cvt_pk_bf16_f32 v33, v34, v35
	v_cvt_pk_bf16_f32 v34, v24, v25
	v_cvt_pk_bf16_f32 v35, v26, v27
	s_nop 1
	v_permlane16_swap_b32_e32 v32, v34
	v_permlane16_swap_b32_e32 v33, v35
	global_store_dwordx4 v[148:149], v[32:35], off
	v_cvt_pk_bf16_f32 v20, v20, v21
	v_cvt_pk_bf16_f32 v21, v22, v23
	v_cvt_pk_bf16_f32 v22, v12, v13
	v_cvt_pk_bf16_f32 v23, v14, v15
	s_nop 1
	v_permlane16_swap_b32_e32 v20, v22
	v_permlane16_swap_b32_e32 v21, v23
	global_store_dwordx4 v[148:149], v[20:23], off offset:256
	v_add_u32_e32 v152, 0xb0, v150
	v_mad_i64_i32 v[148:149], s[24:25], v152, s1, v[140:141]
	v_lshl_add_u64 v[148:149], v[148:149], 0, v[142:143]
	v_cvt_pk_bf16_f32 v16, v16, v17
	v_cvt_pk_bf16_f32 v17, v18, v19
	v_cvt_pk_bf16_f32 v18, v8, v9
	v_cvt_pk_bf16_f32 v19, v10, v11
	s_nop 1
	v_permlane16_swap_b32_e32 v16, v18
	v_permlane16_swap_b32_e32 v17, v19
	global_store_dwordx4 v[148:149], v[16:19], off
	v_cvt_pk_bf16_f32 v4, v4, v5
	v_cvt_pk_bf16_f32 v5, v6, v7
	v_cvt_pk_bf16_f32 v6, v0, v1
	v_cvt_pk_bf16_f32 v7, v2, v3
	s_nop 1
	v_permlane16_swap_b32_e32 v4, v6
	v_permlane16_swap_b32_e32 v5, v7
	global_store_dwordx4 v[148:149], v[4:7], off offset:256
	s_and_b64 vcc, exec, s[38:39]
	s_mov_b32 s30, s0
	s_mov_b32 s31, s2
	s_mov_b64 s[44:45], s[40:41]
	s_mov_b64 s[42:43], s[36:37]
	s_cbranch_vccz .LBB0_363
	s_waitcnt vmcnt(0)
	s_cmpk_gt_u32 s23, 0xff
	s_cbranch_scc1 .LBB0_374
	s_barrier
